# outproj L0/L1 residual epilogues rewritten: 16 residual loads pipelined 8 deep, dwordx4 stores, no per-iteration vmcnt(0)
# speedup vs baseline: 1.1212x; 1.0070x over previous
.LBB0_571:
	s_lshl_b32 s20, s14, 3
	s_and_b32 s21, s19, 7
	s_or_b32 s20, s21, s20
	s_cmpk_gt_u32 s20, 0x203
	s_cbranch_scc1 .LBB0_570
	s_lshl_b32 s15, s15, 7
	s_and_b32 s15, s15, 0x380
	v_or_b32_e32 v0, s15, v157
	v_lshlrev_b32_e32 v64, 11, v0
	v_lshl_add_u64 v[70:71], v[66:67], 0, v[64:65]
	v_lshl_or_b32 v64, s20, 17, v105
	v_lshl_add_u64 v[72:73], v[64:65], 1, v[68:69]
	v_add_co_u32_e32 v74, vcc, s3, v72
	global_load_dwordx4 v[0:3], v[72:73], off
	global_load_dwordx4 v[4:7], v[70:71], off
	v_addc_co_u32_e32 v75, vcc, 0, v73, vcc
	v_add_co_u32_e32 v76, vcc, s3, v70
	global_load_dwordx4 v[8:11], v[74:75], off
	s_nop 0
	v_addc_co_u32_e32 v77, vcc, 0, v71, vcc
	v_add_co_u32_e32 v78, vcc, s16, v72
	global_load_dwordx4 v[12:15], v[76:77], off
	s_nop 0
	v_addc_co_u32_e32 v79, vcc, 0, v73, vcc
	v_add_co_u32_e32 v80, vcc, s16, v70
	global_load_dwordx4 v[16:19], v[78:79], off
	s_nop 0
	v_addc_co_u32_e32 v81, vcc, 0, v71, vcc
	v_add_co_u32_e32 v82, vcc, s17, v72
	v_lshl_add_u64 v[32:33], v[72:73], 0, s[4:5]
	s_nop 0
	v_addc_co_u32_e32 v83, vcc, 0, v73, vcc
	v_add_co_u32_e32 v84, vcc, s17, v70
	v_lshl_add_u64 v[34:35], v[72:73], 0, s[8:9]
	s_nop 0
	v_addc_co_u32_e32 v85, vcc, 0, v71, vcc
	global_load_dwordx4 v[20:23], v[80:81], off
	v_lshl_add_u64 v[36:37], v[72:73], 0, s[12:13]
	global_load_dwordx4 v[24:27], v[82:83], off
	global_load_dwordx4 v[28:31], v[84:85], off
	global_load_dwordx4 v[106:109], v[72:73], off offset:128
	global_load_dwordx4 v[110:113], v[70:71], off offset:128
	global_load_dwordx4 v[114:117], v[32:33], off offset:128
	global_load_dwordx4 v[118:121], v[76:77], off offset:128
	global_load_dwordx4 v[122:125], v[34:35], off offset:128
	global_load_dwordx4 v[126:129], v[80:81], off offset:128
	global_load_dwordx4 v[130:133], v[36:37], off offset:128
	global_load_dwordx4 v[134:137], v[84:85], off offset:128
	s_barrier
	global_load_dwordx4 v[138:141], v[72:73], off offset:256
	global_load_dwordx4 v[142:145], v[70:71], off offset:256
	global_load_dwordx4 v[172:175], v[32:33], off offset:256
	global_load_dwordx4 v[176:179], v[76:77], off offset:256
	global_load_dwordx4 v[180:183], v[34:35], off offset:256
	global_load_dwordx4 v[184:187], v[80:81], off offset:256
	global_load_dwordx4 v[188:191], v[36:37], off offset:256
	global_load_dwordx4 v[192:195], v[84:85], off offset:256
	s_and_b32 s21, s2, 7
	s_lshl_b32 s20, s21, 19
	s_lshl_b32 s22, s21, 7
	s_mov_b32 s21, 0
	s_waitcnt vmcnt(22)
	ds_write_b128 v87, v[4:7] offset:18432
	ds_write_b128 v87, v[0:3]
	s_waitcnt vmcnt(21)
	ds_write_b128 v87, v[8:11] offset:4608
	s_waitcnt vmcnt(20)
	ds_write_b128 v87, v[12:15] offset:23040
	s_waitcnt vmcnt(19)
	ds_write_b128 v87, v[16:19] offset:9216
	s_waitcnt vmcnt(18)
	ds_write_b128 v87, v[20:23] offset:27648
	s_waitcnt vmcnt(17)
	ds_write_b128 v87, v[24:27] offset:13824
	s_waitcnt vmcnt(16)
	ds_write_b128 v87, v[28:31] offset:32256
	s_waitcnt lgkmcnt(0)
	s_barrier
	ds_read_b128 v[0:3], v88
	ds_read_b128 v[4:7], v88 offset:4608
	ds_read_b128 v[8:11], v89 offset:18432
	ds_read_b128 v[12:15], v89 offset:23040
	ds_read_b128 v[196:199], v90 offset:32
	ds_read_b128 v[200:203], v90 offset:4640
	ds_read_b128 v[208:211], v91 offset:18464
	ds_read_b128 v[212:215], v91 offset:23072
	s_waitcnt lgkmcnt(5)
	v_mfma_f32_32x32x16_bf16 v[48:63], v[8:11], v[0:3], 0
	s_waitcnt vmcnt(15)
	ds_write_b128 v87, v[106:109] offset:36864
	s_waitcnt vmcnt(14)
	ds_write_b128 v87, v[110:113] offset:55296
	s_waitcnt vmcnt(13)
	ds_write_b128 v87, v[114:117] offset:41472
	s_waitcnt vmcnt(12)
	ds_write_b128 v87, v[118:121] offset:59904
	s_waitcnt vmcnt(11)
	ds_write_b128 v87, v[122:125] offset:46080
	s_waitcnt vmcnt(10)
	ds_write_b128 v87, v[126:129] offset:64512
	s_waitcnt vmcnt(9)
	ds_write_b128 v87, v[130:133] offset:50688
	s_waitcnt vmcnt(8)
	ds_write_b128 v92, v[134:137] offset:13824
	ds_read_b128 v[106:109], v91 offset:18496
	ds_read_b128 v[110:113], v90 offset:64
	ds_read_b128 v[114:117], v90 offset:96
	ds_read_b128 v[118:121], v91 offset:18528
	ds_read_b128 v[122:125], v91 offset:23104
	ds_read_b128 v[126:129], v91 offset:23136
	s_waitcnt lgkmcnt(14)
	v_mfma_f32_32x32x16_bf16 v[32:47], v[12:15], v[0:3], 0
	v_mfma_f32_32x32x16_bf16 v[16:31], v[8:11], v[4:7], 0
	v_mfma_f32_32x32x16_bf16 v[0:15], v[12:15], v[4:7], 0
	v_mfma_f32_32x32x16_bf16 v[48:63], v[208:211], v[196:199], v[48:63]
	v_mfma_f32_32x32x16_bf16 v[32:47], v[212:215], v[196:199], v[32:47]
	v_mfma_f32_32x32x16_bf16 v[16:31], v[208:211], v[200:203], v[16:31]
	v_mfma_f32_32x32x16_bf16 v[0:15], v[212:215], v[200:203], v[0:15]
	s_waitcnt lgkmcnt(4)
	v_mfma_f32_32x32x16_bf16 v[48:63], v[106:109], v[110:113], v[48:63]
	s_waitcnt lgkmcnt(1)
	v_mfma_f32_32x32x16_bf16 v[32:47], v[122:125], v[110:113], v[32:47]
	ds_read_b128 v[110:113], v90 offset:4672
	ds_read_b128 v[130:133], v90 offset:4704
	s_waitcnt lgkmcnt(1)
	v_mfma_f32_32x32x16_bf16 v[16:31], v[106:109], v[110:113], v[16:31]
	v_mfma_f32_32x32x16_bf16 v[0:15], v[122:125], v[110:113], v[0:15]
	global_load_dwordx4 v[106:109], v[72:73], off offset:384
	global_load_dwordx4 v[110:113], v[70:71], off offset:384
	global_load_dwordx4 v[122:125], v[74:75], off offset:384
	global_load_dwordx4 v[134:137], v[76:77], off offset:384
	global_load_dwordx4 v[196:199], v[78:79], off offset:384
	global_load_dwordx4 v[200:203], v[80:81], off offset:384
	v_mfma_f32_32x32x16_bf16 v[48:63], v[118:121], v[114:117], v[48:63]
	v_mfma_f32_32x32x16_bf16 v[32:47], v[126:129], v[114:117], v[32:47]
	global_load_dwordx4 v[114:117], v[82:83], off offset:384
	global_load_dwordx4 v[208:211], v[84:85], off offset:384
	s_waitcnt lgkmcnt(0)
	s_barrier
	v_mfma_f32_32x32x16_bf16 v[16:31], v[118:121], v[130:133], v[16:31]
	ds_read_b128 v[118:121], v88 offset:36864
	ds_read_b128 v[212:215], v88 offset:41472
	ds_read_b128 v[216:219], v89 offset:55296
	ds_read_b128 v[220:223], v89 offset:59904
	ds_read_b128 v[224:227], v90 offset:36896
	ds_read_b128 v[228:231], v90 offset:41504
	ds_read_b128 v[232:235], v91 offset:55328
	ds_read_b128 v[236:239], v91 offset:59936
	v_mfma_f32_32x32x16_bf16 v[0:15], v[126:129], v[130:133], v[0:15]
	s_waitcnt lgkmcnt(5)
	v_mfma_f32_32x32x16_bf16 v[48:63], v[216:219], v[118:121], v[48:63]
	s_waitcnt vmcnt(15)
	ds_write_b128 v87, v[138:141]
	s_waitcnt vmcnt(14)
	ds_write_b128 v87, v[142:145] offset:18432
	s_waitcnt vmcnt(13)
	ds_write_b128 v87, v[172:175] offset:4608
	s_waitcnt vmcnt(12)
	ds_write_b128 v87, v[176:179] offset:23040
	s_waitcnt vmcnt(11)
	ds_write_b128 v87, v[180:183] offset:9216
	s_waitcnt vmcnt(10)
	ds_write_b128 v87, v[184:187] offset:27648
	s_waitcnt vmcnt(9)
	ds_write_b128 v87, v[188:191] offset:13824
	s_waitcnt vmcnt(8)
	ds_write_b128 v87, v[192:195] offset:32256
	s_waitcnt lgkmcnt(12)
	v_mfma_f32_32x32x16_bf16 v[32:47], v[220:223], v[118:121], v[32:47]
	ds_read_b128 v[118:121], v91 offset:55360
	ds_read_b128 v[126:129], v90 offset:36928
	ds_read_b128 v[130:133], v90 offset:36960
	ds_read_b128 v[138:141], v91 offset:55392
	ds_read_b128 v[142:145], v91 offset:59968
	ds_read_b128 v[172:175], v91 offset:60000
	v_mfma_f32_32x32x16_bf16 v[16:31], v[216:219], v[212:215], v[16:31]
	v_mfma_f32_32x32x16_bf16 v[0:15], v[220:223], v[212:215], v[0:15]
	s_waitcnt lgkmcnt(14)
	v_mfma_f32_32x32x16_bf16 v[48:63], v[232:235], v[224:227], v[48:63]
	v_mfma_f32_32x32x16_bf16 v[32:47], v[236:239], v[224:227], v[32:47]
	v_mfma_f32_32x32x16_bf16 v[16:31], v[232:235], v[228:231], v[16:31]
	v_mfma_f32_32x32x16_bf16 v[0:15], v[236:239], v[228:231], v[0:15]
	s_waitcnt lgkmcnt(4)
	v_mfma_f32_32x32x16_bf16 v[48:63], v[118:121], v[126:129], v[48:63]
	s_waitcnt lgkmcnt(1)
	v_mfma_f32_32x32x16_bf16 v[32:47], v[142:145], v[126:129], v[32:47]
	ds_read_b128 v[126:129], v90 offset:41536
	ds_read_b128 v[176:179], v90 offset:41568
	s_waitcnt lgkmcnt(1)
	v_mfma_f32_32x32x16_bf16 v[16:31], v[118:121], v[126:129], v[16:31]
	v_mfma_f32_32x32x16_bf16 v[0:15], v[142:145], v[126:129], v[0:15]
	global_load_dwordx4 v[118:121], v[72:73], off offset:512
	global_load_dwordx4 v[126:129], v[70:71], off offset:512
	global_load_dwordx4 v[142:145], v[74:75], off offset:512
	global_load_dwordx4 v[180:183], v[76:77], off offset:512
	global_load_dwordx4 v[184:187], v[78:79], off offset:512
	global_load_dwordx4 v[188:191], v[80:81], off offset:512
	v_mfma_f32_32x32x16_bf16 v[48:63], v[138:141], v[130:133], v[48:63]
	v_mfma_f32_32x32x16_bf16 v[32:47], v[172:175], v[130:133], v[32:47]
	global_load_dwordx4 v[130:133], v[82:83], off offset:512
	global_load_dwordx4 v[192:195], v[84:85], off offset:512
	s_waitcnt lgkmcnt(0)
	s_barrier
	v_mfma_f32_32x32x16_bf16 v[16:31], v[138:141], v[176:179], v[16:31]
	ds_read_b128 v[138:141], v88
	ds_read_b128 v[212:215], v88 offset:4608
	ds_read_b128 v[216:219], v89 offset:18432
	ds_read_b128 v[220:223], v89 offset:23040
	ds_read_b128 v[224:227], v90 offset:32
	ds_read_b128 v[228:231], v90 offset:4640
	ds_read_b128 v[232:235], v91 offset:18464
	ds_read_b128 v[236:239], v91 offset:23072
	v_mfma_f32_32x32x16_bf16 v[0:15], v[172:175], v[176:179], v[0:15]
	s_waitcnt lgkmcnt(5)
	v_mfma_f32_32x32x16_bf16 v[48:63], v[216:219], v[138:141], v[48:63]
	s_waitcnt vmcnt(15)
	ds_write_b128 v87, v[106:109] offset:36864
	s_waitcnt vmcnt(14)
	ds_write_b128 v87, v[110:113] offset:55296
	s_waitcnt vmcnt(13)
	ds_write_b128 v87, v[122:125] offset:41472
	s_waitcnt vmcnt(12)
	ds_write_b128 v87, v[134:137] offset:59904
	s_waitcnt vmcnt(11)
	ds_write_b128 v87, v[196:199] offset:46080
	s_waitcnt vmcnt(10)
	ds_write_b128 v87, v[200:203] offset:64512
	s_waitcnt vmcnt(9)
	ds_write_b128 v87, v[114:117] offset:50688
	s_waitcnt vmcnt(8)
	ds_write_b128 v92, v[208:211] offset:13824
	ds_read_b128 v[106:109], v91 offset:18496
	ds_read_b128 v[110:113], v90 offset:64
	ds_read_b128 v[114:117], v90 offset:96
	ds_read_b128 v[122:125], v91 offset:18528
	s_waitcnt lgkmcnt(14)
	v_mfma_f32_32x32x16_bf16 v[32:47], v[220:223], v[138:141], v[32:47]
	ds_read_b128 v[134:137], v91 offset:23104
	ds_read_b128 v[138:141], v91 offset:23136
	v_mfma_f32_32x32x16_bf16 v[16:31], v[216:219], v[212:215], v[16:31]
	v_mfma_f32_32x32x16_bf16 v[0:15], v[220:223], v[212:215], v[0:15]
	s_waitcnt lgkmcnt(14)
	v_mfma_f32_32x32x16_bf16 v[48:63], v[232:235], v[224:227], v[48:63]
	v_mfma_f32_32x32x16_bf16 v[32:47], v[236:239], v[224:227], v[32:47]
	v_mfma_f32_32x32x16_bf16 v[16:31], v[232:235], v[228:231], v[16:31]
	v_mfma_f32_32x32x16_bf16 v[0:15], v[236:239], v[228:231], v[0:15]
	s_waitcnt lgkmcnt(4)
	v_mfma_f32_32x32x16_bf16 v[48:63], v[106:109], v[110:113], v[48:63]
	s_waitcnt lgkmcnt(1)
	v_mfma_f32_32x32x16_bf16 v[32:47], v[134:137], v[110:113], v[32:47]
	ds_read_b128 v[110:113], v90 offset:4672
	ds_read_b128 v[172:175], v90 offset:4704
	s_waitcnt lgkmcnt(1)
	v_mfma_f32_32x32x16_bf16 v[16:31], v[106:109], v[110:113], v[16:31]
	v_mfma_f32_32x32x16_bf16 v[0:15], v[134:137], v[110:113], v[0:15]
	global_load_dwordx4 v[106:109], v[72:73], off offset:640
	global_load_dwordx4 v[110:113], v[70:71], off offset:640
	global_load_dwordx4 v[134:137], v[74:75], off offset:640
	global_load_dwordx4 v[176:179], v[76:77], off offset:640
	global_load_dwordx4 v[196:199], v[78:79], off offset:640
	global_load_dwordx4 v[200:203], v[80:81], off offset:640
	v_mfma_f32_32x32x16_bf16 v[48:63], v[122:125], v[114:117], v[48:63]
	v_mfma_f32_32x32x16_bf16 v[32:47], v[138:141], v[114:117], v[32:47]
	global_load_dwordx4 v[114:117], v[82:83], off offset:640
	global_load_dwordx4 v[208:211], v[84:85], off offset:640
	s_waitcnt lgkmcnt(0)
	s_barrier
	v_mfma_f32_32x32x16_bf16 v[16:31], v[122:125], v[172:175], v[16:31]
	ds_read_b128 v[122:125], v88 offset:36864
	ds_read_b128 v[212:215], v88 offset:41472
	ds_read_b128 v[216:219], v89 offset:55296
	ds_read_b128 v[220:223], v89 offset:59904
	ds_read_b128 v[224:227], v90 offset:36896
	ds_read_b128 v[228:231], v90 offset:41504
	ds_read_b128 v[232:235], v91 offset:55328
	ds_read_b128 v[236:239], v91 offset:59936
	v_mfma_f32_32x32x16_bf16 v[0:15], v[138:141], v[172:175], v[0:15]
	s_waitcnt lgkmcnt(5)
	v_mfma_f32_32x32x16_bf16 v[48:63], v[216:219], v[122:125], v[48:63]
	s_waitcnt vmcnt(15)
	ds_write_b128 v87, v[118:121]
	s_waitcnt vmcnt(14)
	ds_write_b128 v87, v[126:129] offset:18432
	s_waitcnt vmcnt(13)
	ds_write_b128 v87, v[142:145] offset:4608
	s_waitcnt vmcnt(12)
	ds_write_b128 v87, v[180:183] offset:23040
	s_waitcnt vmcnt(11)
	ds_write_b128 v87, v[184:187] offset:9216
	s_waitcnt vmcnt(10)
	ds_write_b128 v87, v[188:191] offset:27648
	s_waitcnt vmcnt(9)
	ds_write_b128 v87, v[130:133] offset:13824
	s_waitcnt vmcnt(8)
	ds_write_b128 v87, v[192:195] offset:32256
	s_waitcnt lgkmcnt(12)
	v_mfma_f32_32x32x16_bf16 v[32:47], v[220:223], v[122:125], v[32:47]
	ds_read_b128 v[118:121], v91 offset:55360
	ds_read_b128 v[122:125], v90 offset:36928
	ds_read_b128 v[126:129], v90 offset:36960
	ds_read_b128 v[130:133], v91 offset:55392
	ds_read_b128 v[138:141], v91 offset:59968
	ds_read_b128 v[142:145], v91 offset:60000
	v_mfma_f32_32x32x16_bf16 v[16:31], v[216:219], v[212:215], v[16:31]
	v_mfma_f32_32x32x16_bf16 v[0:15], v[220:223], v[212:215], v[0:15]
	s_waitcnt lgkmcnt(14)
	v_mfma_f32_32x32x16_bf16 v[48:63], v[232:235], v[224:227], v[48:63]
	v_mfma_f32_32x32x16_bf16 v[32:47], v[236:239], v[224:227], v[32:47]
	v_mfma_f32_32x32x16_bf16 v[16:31], v[232:235], v[228:231], v[16:31]
	v_mfma_f32_32x32x16_bf16 v[0:15], v[236:239], v[228:231], v[0:15]
	s_waitcnt lgkmcnt(4)
	v_mfma_f32_32x32x16_bf16 v[48:63], v[118:121], v[122:125], v[48:63]
	s_waitcnt lgkmcnt(1)
	v_mfma_f32_32x32x16_bf16 v[32:47], v[138:141], v[122:125], v[32:47]
	ds_read_b128 v[122:125], v90 offset:41536
	ds_read_b128 v[172:175], v90 offset:41568
	s_waitcnt lgkmcnt(1)
	v_mfma_f32_32x32x16_bf16 v[16:31], v[118:121], v[122:125], v[16:31]
	v_mfma_f32_32x32x16_bf16 v[0:15], v[138:141], v[122:125], v[0:15]
	global_load_dwordx4 v[118:121], v[72:73], off offset:768
	global_load_dwordx4 v[122:125], v[70:71], off offset:768
	global_load_dwordx4 v[138:141], v[74:75], off offset:768
	global_load_dwordx4 v[180:183], v[76:77], off offset:768
	global_load_dwordx4 v[184:187], v[78:79], off offset:768
	global_load_dwordx4 v[188:191], v[80:81], off offset:768
	v_mfma_f32_32x32x16_bf16 v[48:63], v[130:133], v[126:129], v[48:63]
	v_mfma_f32_32x32x16_bf16 v[32:47], v[142:145], v[126:129], v[32:47]
	global_load_dwordx4 v[126:129], v[82:83], off offset:768
	global_load_dwordx4 v[192:195], v[84:85], off offset:768
	s_waitcnt lgkmcnt(0)
	s_barrier
	v_mfma_f32_32x32x16_bf16 v[16:31], v[130:133], v[172:175], v[16:31]
	ds_read_b128 v[130:133], v88
	ds_read_b128 v[212:215], v88 offset:4608
	ds_read_b128 v[216:219], v89 offset:18432
	ds_read_b128 v[220:223], v89 offset:23040
	ds_read_b128 v[224:227], v90 offset:32
	ds_read_b128 v[228:231], v90 offset:4640
	ds_read_b128 v[232:235], v91 offset:18464
	ds_read_b128 v[236:239], v91 offset:23072
	v_mfma_f32_32x32x16_bf16 v[0:15], v[142:145], v[172:175], v[0:15]
	s_waitcnt lgkmcnt(5)
	v_mfma_f32_32x32x16_bf16 v[48:63], v[216:219], v[130:133], v[48:63]
	s_waitcnt vmcnt(15)
	ds_write_b128 v87, v[106:109] offset:36864
	s_waitcnt vmcnt(14)
	ds_write_b128 v87, v[110:113] offset:55296
	s_waitcnt vmcnt(13)
	ds_write_b128 v87, v[134:137] offset:41472
	s_waitcnt vmcnt(12)
	ds_write_b128 v87, v[176:179] offset:59904
	s_waitcnt vmcnt(11)
	ds_write_b128 v87, v[196:199] offset:46080
	s_waitcnt vmcnt(10)
	ds_write_b128 v87, v[200:203] offset:64512
	s_waitcnt vmcnt(9)
	ds_write_b128 v87, v[114:117] offset:50688
	s_waitcnt vmcnt(8)
	ds_write_b128 v92, v[208:211] offset:13824
	s_waitcnt lgkmcnt(12)
	v_mfma_f32_32x32x16_bf16 v[32:47], v[220:223], v[130:133], v[32:47]
	ds_read_b128 v[106:109], v91 offset:18496
	ds_read_b128 v[110:113], v90 offset:64
	ds_read_b128 v[114:117], v90 offset:96
	ds_read_b128 v[130:133], v91 offset:18528
	ds_read_b128 v[134:137], v91 offset:23104
	ds_read_b128 v[142:145], v91 offset:23136
	v_mfma_f32_32x32x16_bf16 v[16:31], v[216:219], v[212:215], v[16:31]
	v_mfma_f32_32x32x16_bf16 v[0:15], v[220:223], v[212:215], v[0:15]
	s_waitcnt lgkmcnt(14)
	v_mfma_f32_32x32x16_bf16 v[48:63], v[232:235], v[224:227], v[48:63]
	v_mfma_f32_32x32x16_bf16 v[32:47], v[236:239], v[224:227], v[32:47]
	v_mfma_f32_32x32x16_bf16 v[16:31], v[232:235], v[228:231], v[16:31]
	v_mfma_f32_32x32x16_bf16 v[0:15], v[236:239], v[228:231], v[0:15]
	s_waitcnt lgkmcnt(4)
	v_mfma_f32_32x32x16_bf16 v[48:63], v[106:109], v[110:113], v[48:63]
	s_waitcnt lgkmcnt(1)
	v_mfma_f32_32x32x16_bf16 v[32:47], v[134:137], v[110:113], v[32:47]
	ds_read_b128 v[110:113], v90 offset:4672
	ds_read_b128 v[172:175], v90 offset:4704
	s_waitcnt lgkmcnt(1)
	v_mfma_f32_32x32x16_bf16 v[16:31], v[106:109], v[110:113], v[16:31]
	v_mfma_f32_32x32x16_bf16 v[0:15], v[134:137], v[110:113], v[0:15]
	global_load_dwordx4 v[106:109], v[72:73], off offset:896
	global_load_dwordx4 v[110:113], v[70:71], off offset:896
	global_load_dwordx4 v[134:137], v[74:75], off offset:896
	global_load_dwordx4 v[176:179], v[76:77], off offset:896
	global_load_dwordx4 v[196:199], v[78:79], off offset:896
	global_load_dwordx4 v[200:203], v[80:81], off offset:896
	v_mfma_f32_32x32x16_bf16 v[48:63], v[130:133], v[114:117], v[48:63]
	v_mfma_f32_32x32x16_bf16 v[32:47], v[142:145], v[114:117], v[32:47]
	global_load_dwordx4 v[114:117], v[82:83], off offset:896
	global_load_dwordx4 v[208:211], v[84:85], off offset:896
	s_waitcnt lgkmcnt(0)
	s_barrier
	v_mfma_f32_32x32x16_bf16 v[16:31], v[130:133], v[172:175], v[16:31]
	ds_read_b128 v[130:133], v88 offset:36864
	ds_read_b128 v[212:215], v88 offset:41472
	ds_read_b128 v[216:219], v89 offset:55296
	ds_read_b128 v[220:223], v89 offset:59904
	ds_read_b128 v[224:227], v90 offset:36896
	ds_read_b128 v[228:231], v90 offset:41504
	ds_read_b128 v[232:235], v91 offset:55328
	ds_read_b128 v[236:239], v91 offset:59936
	v_mfma_f32_32x32x16_bf16 v[0:15], v[142:145], v[172:175], v[0:15]
	s_waitcnt lgkmcnt(5)
	v_mfma_f32_32x32x16_bf16 v[48:63], v[216:219], v[130:133], v[48:63]
	s_waitcnt vmcnt(15)
	ds_write_b128 v87, v[118:121]
	s_waitcnt vmcnt(14)
	ds_write_b128 v87, v[122:125] offset:18432
	s_waitcnt vmcnt(13)
	ds_write_b128 v87, v[138:141] offset:4608
	s_waitcnt vmcnt(12)
	ds_write_b128 v87, v[180:183] offset:23040
	s_waitcnt vmcnt(11)
	ds_write_b128 v87, v[184:187] offset:9216
	s_waitcnt vmcnt(10)
	ds_write_b128 v87, v[188:191] offset:27648
	s_waitcnt vmcnt(9)
	ds_write_b128 v87, v[126:129] offset:13824
	s_waitcnt vmcnt(8)
	ds_write_b128 v87, v[192:195] offset:32256
	s_waitcnt lgkmcnt(12)
	v_mfma_f32_32x32x16_bf16 v[32:47], v[220:223], v[130:133], v[32:47]
	ds_read_b128 v[118:121], v91 offset:55360
	ds_read_b128 v[122:125], v90 offset:36928
	ds_read_b128 v[126:129], v90 offset:36960
	ds_read_b128 v[130:133], v91 offset:55392
	ds_read_b128 v[138:141], v91 offset:59968
	ds_read_b128 v[142:145], v91 offset:60000
	v_mfma_f32_32x32x16_bf16 v[16:31], v[216:219], v[212:215], v[16:31]
	v_mfma_f32_32x32x16_bf16 v[0:15], v[220:223], v[212:215], v[0:15]
	s_waitcnt lgkmcnt(14)
	v_mfma_f32_32x32x16_bf16 v[48:63], v[232:235], v[224:227], v[48:63]
	v_mfma_f32_32x32x16_bf16 v[32:47], v[236:239], v[224:227], v[32:47]
	v_mfma_f32_32x32x16_bf16 v[16:31], v[232:235], v[228:231], v[16:31]
	v_mfma_f32_32x32x16_bf16 v[0:15], v[236:239], v[228:231], v[0:15]
	s_waitcnt lgkmcnt(4)
	v_mfma_f32_32x32x16_bf16 v[48:63], v[118:121], v[122:125], v[48:63]
	s_waitcnt lgkmcnt(1)
	v_mfma_f32_32x32x16_bf16 v[32:47], v[138:141], v[122:125], v[32:47]
	ds_read_b128 v[122:125], v90 offset:41536
	ds_read_b128 v[172:175], v90 offset:41568
	s_waitcnt lgkmcnt(1)
	v_mfma_f32_32x32x16_bf16 v[16:31], v[118:121], v[122:125], v[16:31]
	v_mfma_f32_32x32x16_bf16 v[0:15], v[138:141], v[122:125], v[0:15]
	global_load_dwordx4 v[118:121], v[72:73], off offset:1024
	global_load_dwordx4 v[122:125], v[70:71], off offset:1024
	global_load_dwordx4 v[138:141], v[74:75], off offset:1024
	global_load_dwordx4 v[180:183], v[76:77], off offset:1024
	global_load_dwordx4 v[184:187], v[78:79], off offset:1024
	global_load_dwordx4 v[188:191], v[80:81], off offset:1024
	v_mfma_f32_32x32x16_bf16 v[48:63], v[130:133], v[126:129], v[48:63]
	v_mfma_f32_32x32x16_bf16 v[32:47], v[142:145], v[126:129], v[32:47]
	global_load_dwordx4 v[126:129], v[82:83], off offset:1024
	global_load_dwordx4 v[192:195], v[84:85], off offset:1024
	s_waitcnt lgkmcnt(0)
	s_barrier
	v_mfma_f32_32x32x16_bf16 v[16:31], v[130:133], v[172:175], v[16:31]
	ds_read_b128 v[130:133], v88
	ds_read_b128 v[212:215], v88 offset:4608
	ds_read_b128 v[216:219], v89 offset:18432
	ds_read_b128 v[220:223], v89 offset:23040
	ds_read_b128 v[224:227], v90 offset:32
	ds_read_b128 v[228:231], v90 offset:4640
	ds_read_b128 v[232:235], v91 offset:18464
	ds_read_b128 v[236:239], v91 offset:23072
	v_mfma_f32_32x32x16_bf16 v[0:15], v[142:145], v[172:175], v[0:15]
	s_waitcnt lgkmcnt(5)
	v_mfma_f32_32x32x16_bf16 v[48:63], v[216:219], v[130:133], v[48:63]
	s_waitcnt vmcnt(15)
	ds_write_b128 v87, v[106:109] offset:36864
	s_waitcnt vmcnt(14)
	ds_write_b128 v87, v[110:113] offset:55296
	s_waitcnt vmcnt(13)
	ds_write_b128 v87, v[134:137] offset:41472
	s_waitcnt vmcnt(12)
	ds_write_b128 v87, v[176:179] offset:59904
	s_waitcnt vmcnt(11)
	ds_write_b128 v87, v[196:199] offset:46080
	s_waitcnt vmcnt(10)
	ds_write_b128 v87, v[200:203] offset:64512
	s_waitcnt vmcnt(9)
	ds_write_b128 v87, v[114:117] offset:50688
	s_waitcnt vmcnt(8)
	ds_write_b128 v92, v[208:211] offset:13824
	s_waitcnt lgkmcnt(12)
	v_mfma_f32_32x32x16_bf16 v[32:47], v[220:223], v[130:133], v[32:47]
	ds_read_b128 v[106:109], v91 offset:18496
	ds_read_b128 v[110:113], v90 offset:64
	ds_read_b128 v[114:117], v90 offset:96
	ds_read_b128 v[130:133], v91 offset:18528
	ds_read_b128 v[134:137], v91 offset:23104
	ds_read_b128 v[142:145], v91 offset:23136
	v_mfma_f32_32x32x16_bf16 v[16:31], v[216:219], v[212:215], v[16:31]
	v_mfma_f32_32x32x16_bf16 v[0:15], v[220:223], v[212:215], v[0:15]
	s_waitcnt lgkmcnt(14)
	v_mfma_f32_32x32x16_bf16 v[48:63], v[232:235], v[224:227], v[48:63]
	v_mfma_f32_32x32x16_bf16 v[32:47], v[236:239], v[224:227], v[32:47]
	v_mfma_f32_32x32x16_bf16 v[16:31], v[232:235], v[228:231], v[16:31]
	v_mfma_f32_32x32x16_bf16 v[0:15], v[236:239], v[228:231], v[0:15]
	s_waitcnt lgkmcnt(4)
	v_mfma_f32_32x32x16_bf16 v[48:63], v[106:109], v[110:113], v[48:63]
	s_waitcnt lgkmcnt(1)
	v_mfma_f32_32x32x16_bf16 v[32:47], v[134:137], v[110:113], v[32:47]
	ds_read_b128 v[110:113], v90 offset:4672
	ds_read_b128 v[172:175], v90 offset:4704
	s_waitcnt lgkmcnt(1)
	v_mfma_f32_32x32x16_bf16 v[16:31], v[106:109], v[110:113], v[16:31]
	v_mfma_f32_32x32x16_bf16 v[0:15], v[134:137], v[110:113], v[0:15]
	global_load_dwordx4 v[106:109], v[72:73], off offset:1152
	global_load_dwordx4 v[110:113], v[70:71], off offset:1152
	global_load_dwordx4 v[134:137], v[74:75], off offset:1152
	global_load_dwordx4 v[176:179], v[76:77], off offset:1152
	global_load_dwordx4 v[196:199], v[78:79], off offset:1152
	global_load_dwordx4 v[200:203], v[80:81], off offset:1152
	v_mfma_f32_32x32x16_bf16 v[48:63], v[130:133], v[114:117], v[48:63]
	v_mfma_f32_32x32x16_bf16 v[32:47], v[142:145], v[114:117], v[32:47]
	global_load_dwordx4 v[114:117], v[82:83], off offset:1152
	global_load_dwordx4 v[208:211], v[84:85], off offset:1152
	s_waitcnt lgkmcnt(0)
	s_barrier
	v_mfma_f32_32x32x16_bf16 v[16:31], v[130:133], v[172:175], v[16:31]
	ds_read_b128 v[130:133], v88 offset:36864
	ds_read_b128 v[212:215], v88 offset:41472
	ds_read_b128 v[216:219], v89 offset:55296
	ds_read_b128 v[220:223], v89 offset:59904
	ds_read_b128 v[224:227], v90 offset:36896
	ds_read_b128 v[228:231], v90 offset:41504
	ds_read_b128 v[232:235], v91 offset:55328
	ds_read_b128 v[236:239], v91 offset:59936
	v_mfma_f32_32x32x16_bf16 v[0:15], v[142:145], v[172:175], v[0:15]
	s_waitcnt lgkmcnt(5)
	v_mfma_f32_32x32x16_bf16 v[48:63], v[216:219], v[130:133], v[48:63]
	s_waitcnt vmcnt(15)
	ds_write_b128 v87, v[118:121]
	s_waitcnt vmcnt(14)
	ds_write_b128 v87, v[122:125] offset:18432
	s_waitcnt vmcnt(13)
	ds_write_b128 v87, v[138:141] offset:4608
	s_waitcnt vmcnt(12)
	ds_write_b128 v87, v[180:183] offset:23040
	s_waitcnt vmcnt(11)
	ds_write_b128 v87, v[184:187] offset:9216
	s_waitcnt vmcnt(10)
	ds_write_b128 v87, v[188:191] offset:27648
	s_waitcnt vmcnt(9)
	ds_write_b128 v87, v[126:129] offset:13824
	s_waitcnt vmcnt(8)
	ds_write_b128 v87, v[192:195] offset:32256
	s_waitcnt lgkmcnt(12)
	v_mfma_f32_32x32x16_bf16 v[32:47], v[220:223], v[130:133], v[32:47]
	ds_read_b128 v[118:121], v91 offset:55360
	ds_read_b128 v[122:125], v90 offset:36928
	ds_read_b128 v[126:129], v90 offset:36960
	ds_read_b128 v[130:133], v91 offset:55392
	ds_read_b128 v[138:141], v91 offset:59968
	ds_read_b128 v[142:145], v91 offset:60000
	v_mfma_f32_32x32x16_bf16 v[16:31], v[216:219], v[212:215], v[16:31]
	v_mfma_f32_32x32x16_bf16 v[0:15], v[220:223], v[212:215], v[0:15]
	s_waitcnt lgkmcnt(14)
	v_mfma_f32_32x32x16_bf16 v[48:63], v[232:235], v[224:227], v[48:63]
	v_mfma_f32_32x32x16_bf16 v[32:47], v[236:239], v[224:227], v[32:47]
	v_mfma_f32_32x32x16_bf16 v[16:31], v[232:235], v[228:231], v[16:31]
	v_mfma_f32_32x32x16_bf16 v[0:15], v[236:239], v[228:231], v[0:15]
	s_waitcnt lgkmcnt(4)
	v_mfma_f32_32x32x16_bf16 v[48:63], v[118:121], v[122:125], v[48:63]
	s_waitcnt lgkmcnt(1)
	v_mfma_f32_32x32x16_bf16 v[32:47], v[138:141], v[122:125], v[32:47]
	ds_read_b128 v[122:125], v90 offset:41536
	ds_read_b128 v[172:175], v90 offset:41568
	s_waitcnt lgkmcnt(1)
	v_mfma_f32_32x32x16_bf16 v[16:31], v[118:121], v[122:125], v[16:31]
	v_mfma_f32_32x32x16_bf16 v[0:15], v[138:141], v[122:125], v[0:15]
	global_load_dwordx4 v[118:121], v[72:73], off offset:1280
	global_load_dwordx4 v[122:125], v[70:71], off offset:1280
	global_load_dwordx4 v[138:141], v[74:75], off offset:1280
	global_load_dwordx4 v[180:183], v[76:77], off offset:1280
	global_load_dwordx4 v[184:187], v[78:79], off offset:1280
	global_load_dwordx4 v[188:191], v[80:81], off offset:1280
	v_mfma_f32_32x32x16_bf16 v[48:63], v[130:133], v[126:129], v[48:63]
	v_mfma_f32_32x32x16_bf16 v[32:47], v[142:145], v[126:129], v[32:47]
	global_load_dwordx4 v[126:129], v[82:83], off offset:1280
	global_load_dwordx4 v[192:195], v[84:85], off offset:1280
	s_waitcnt lgkmcnt(0)
	s_barrier
	v_mfma_f32_32x32x16_bf16 v[16:31], v[130:133], v[172:175], v[16:31]
	ds_read_b128 v[130:133], v88
	ds_read_b128 v[212:215], v88 offset:4608
	ds_read_b128 v[216:219], v89 offset:18432
	ds_read_b128 v[220:223], v89 offset:23040
	ds_read_b128 v[224:227], v90 offset:32
	ds_read_b128 v[228:231], v90 offset:4640
	ds_read_b128 v[232:235], v91 offset:18464
	ds_read_b128 v[236:239], v91 offset:23072
	v_mfma_f32_32x32x16_bf16 v[0:15], v[142:145], v[172:175], v[0:15]
	s_waitcnt lgkmcnt(5)
	v_mfma_f32_32x32x16_bf16 v[48:63], v[216:219], v[130:133], v[48:63]
	s_waitcnt vmcnt(15)
	ds_write_b128 v87, v[106:109] offset:36864
	s_waitcnt vmcnt(14)
	ds_write_b128 v87, v[110:113] offset:55296
	s_waitcnt vmcnt(13)
	ds_write_b128 v87, v[134:137] offset:41472
	s_waitcnt vmcnt(12)
	ds_write_b128 v87, v[176:179] offset:59904
	s_waitcnt vmcnt(11)
	ds_write_b128 v87, v[196:199] offset:46080
	s_waitcnt vmcnt(10)
	ds_write_b128 v87, v[200:203] offset:64512
	s_waitcnt vmcnt(9)
	ds_write_b128 v87, v[114:117] offset:50688
	s_waitcnt vmcnt(8)
	ds_write_b128 v92, v[208:211] offset:13824
	s_waitcnt lgkmcnt(12)
	v_mfma_f32_32x32x16_bf16 v[32:47], v[220:223], v[130:133], v[32:47]
	ds_read_b128 v[106:109], v91 offset:18496
	ds_read_b128 v[110:113], v90 offset:64
	ds_read_b128 v[114:117], v90 offset:96
	ds_read_b128 v[130:133], v91 offset:18528
	ds_read_b128 v[134:137], v91 offset:23104
	ds_read_b128 v[142:145], v91 offset:23136
	v_mfma_f32_32x32x16_bf16 v[16:31], v[216:219], v[212:215], v[16:31]
	v_mfma_f32_32x32x16_bf16 v[0:15], v[220:223], v[212:215], v[0:15]
	s_waitcnt lgkmcnt(14)
	v_mfma_f32_32x32x16_bf16 v[48:63], v[232:235], v[224:227], v[48:63]
	v_mfma_f32_32x32x16_bf16 v[32:47], v[236:239], v[224:227], v[32:47]
	v_mfma_f32_32x32x16_bf16 v[16:31], v[232:235], v[228:231], v[16:31]
	v_mfma_f32_32x32x16_bf16 v[0:15], v[236:239], v[228:231], v[0:15]
	s_waitcnt lgkmcnt(4)
	v_mfma_f32_32x32x16_bf16 v[48:63], v[106:109], v[110:113], v[48:63]
	s_waitcnt lgkmcnt(1)
	v_mfma_f32_32x32x16_bf16 v[32:47], v[134:137], v[110:113], v[32:47]
	ds_read_b128 v[110:113], v90 offset:4672
	ds_read_b128 v[172:175], v90 offset:4704
	s_waitcnt lgkmcnt(1)
	v_mfma_f32_32x32x16_bf16 v[16:31], v[106:109], v[110:113], v[16:31]
	v_mfma_f32_32x32x16_bf16 v[0:15], v[134:137], v[110:113], v[0:15]
	global_load_dwordx4 v[106:109], v[72:73], off offset:1408
	global_load_dwordx4 v[110:113], v[70:71], off offset:1408
	global_load_dwordx4 v[134:137], v[74:75], off offset:1408
	global_load_dwordx4 v[176:179], v[76:77], off offset:1408
	global_load_dwordx4 v[196:199], v[78:79], off offset:1408
	global_load_dwordx4 v[200:203], v[80:81], off offset:1408
	v_mfma_f32_32x32x16_bf16 v[48:63], v[130:133], v[114:117], v[48:63]
	v_mfma_f32_32x32x16_bf16 v[32:47], v[142:145], v[114:117], v[32:47]
	global_load_dwordx4 v[114:117], v[82:83], off offset:1408
	global_load_dwordx4 v[208:211], v[84:85], off offset:1408
	s_waitcnt lgkmcnt(0)
	s_barrier
	v_mfma_f32_32x32x16_bf16 v[16:31], v[130:133], v[172:175], v[16:31]
	ds_read_b128 v[130:133], v88 offset:36864
	ds_read_b128 v[212:215], v88 offset:41472
	ds_read_b128 v[216:219], v89 offset:55296
	ds_read_b128 v[220:223], v89 offset:59904
	ds_read_b128 v[224:227], v90 offset:36896
	ds_read_b128 v[228:231], v90 offset:41504
	ds_read_b128 v[232:235], v91 offset:55328
	ds_read_b128 v[236:239], v91 offset:59936
	v_mfma_f32_32x32x16_bf16 v[0:15], v[142:145], v[172:175], v[0:15]
	s_waitcnt lgkmcnt(5)
	v_mfma_f32_32x32x16_bf16 v[48:63], v[216:219], v[130:133], v[48:63]
	s_waitcnt vmcnt(15)
	ds_write_b128 v87, v[118:121]
	s_waitcnt vmcnt(14)
	ds_write_b128 v87, v[122:125] offset:18432
	s_waitcnt vmcnt(13)
	ds_write_b128 v87, v[138:141] offset:4608
	s_waitcnt vmcnt(12)
	ds_write_b128 v87, v[180:183] offset:23040
	s_waitcnt vmcnt(11)
	ds_write_b128 v87, v[184:187] offset:9216
	s_waitcnt vmcnt(10)
	ds_write_b128 v87, v[188:191] offset:27648
	s_waitcnt vmcnt(9)
	ds_write_b128 v87, v[126:129] offset:13824
	s_waitcnt vmcnt(8)
	ds_write_b128 v87, v[192:195] offset:32256
	s_waitcnt lgkmcnt(12)
	v_mfma_f32_32x32x16_bf16 v[32:47], v[220:223], v[130:133], v[32:47]
	ds_read_b128 v[118:121], v91 offset:55360
	ds_read_b128 v[122:125], v90 offset:36928
	ds_read_b128 v[126:129], v90 offset:36960
	ds_read_b128 v[130:133], v91 offset:55392
	ds_read_b128 v[138:141], v91 offset:59968
	ds_read_b128 v[142:145], v91 offset:60000
	v_mfma_f32_32x32x16_bf16 v[16:31], v[216:219], v[212:215], v[16:31]
	v_mfma_f32_32x32x16_bf16 v[0:15], v[220:223], v[212:215], v[0:15]
	s_waitcnt lgkmcnt(14)
	v_mfma_f32_32x32x16_bf16 v[48:63], v[232:235], v[224:227], v[48:63]
	v_mfma_f32_32x32x16_bf16 v[32:47], v[236:239], v[224:227], v[32:47]
	v_mfma_f32_32x32x16_bf16 v[16:31], v[232:235], v[228:231], v[16:31]
	v_mfma_f32_32x32x16_bf16 v[0:15], v[236:239], v[228:231], v[0:15]
	s_waitcnt lgkmcnt(4)
	v_mfma_f32_32x32x16_bf16 v[48:63], v[118:121], v[122:125], v[48:63]
	s_waitcnt lgkmcnt(1)
	v_mfma_f32_32x32x16_bf16 v[32:47], v[138:141], v[122:125], v[32:47]
	ds_read_b128 v[122:125], v90 offset:41536
	ds_read_b128 v[172:175], v90 offset:41568
	s_waitcnt lgkmcnt(1)
	v_mfma_f32_32x32x16_bf16 v[16:31], v[118:121], v[122:125], v[16:31]
	v_mfma_f32_32x32x16_bf16 v[0:15], v[138:141], v[122:125], v[0:15]
	global_load_dwordx4 v[118:121], v[72:73], off offset:1536
	global_load_dwordx4 v[122:125], v[70:71], off offset:1536
	global_load_dwordx4 v[138:141], v[74:75], off offset:1536
	global_load_dwordx4 v[180:183], v[76:77], off offset:1536
	global_load_dwordx4 v[184:187], v[78:79], off offset:1536
	global_load_dwordx4 v[188:191], v[80:81], off offset:1536
	v_mfma_f32_32x32x16_bf16 v[48:63], v[130:133], v[126:129], v[48:63]
	v_mfma_f32_32x32x16_bf16 v[32:47], v[142:145], v[126:129], v[32:47]
	global_load_dwordx4 v[126:129], v[82:83], off offset:1536
	global_load_dwordx4 v[192:195], v[84:85], off offset:1536
	s_waitcnt lgkmcnt(0)
	s_barrier
	v_mfma_f32_32x32x16_bf16 v[16:31], v[130:133], v[172:175], v[16:31]
	ds_read_b128 v[130:133], v88
	ds_read_b128 v[212:215], v88 offset:4608
	ds_read_b128 v[216:219], v89 offset:18432
	ds_read_b128 v[220:223], v89 offset:23040
	ds_read_b128 v[224:227], v90 offset:32
	ds_read_b128 v[228:231], v90 offset:4640
	ds_read_b128 v[232:235], v91 offset:18464
	ds_read_b128 v[236:239], v91 offset:23072
	v_mfma_f32_32x32x16_bf16 v[0:15], v[142:145], v[172:175], v[0:15]
	s_waitcnt lgkmcnt(5)
	v_mfma_f32_32x32x16_bf16 v[48:63], v[216:219], v[130:133], v[48:63]
	s_waitcnt vmcnt(15)
	ds_write_b128 v87, v[106:109] offset:36864
	s_waitcnt vmcnt(14)
	ds_write_b128 v87, v[110:113] offset:55296
	s_waitcnt vmcnt(13)
	ds_write_b128 v87, v[134:137] offset:41472
	s_waitcnt vmcnt(12)
	ds_write_b128 v87, v[176:179] offset:59904
	s_waitcnt vmcnt(11)
	ds_write_b128 v87, v[196:199] offset:46080
	s_waitcnt vmcnt(10)
	ds_write_b128 v87, v[200:203] offset:64512
	s_waitcnt vmcnt(9)
	ds_write_b128 v87, v[114:117] offset:50688
	s_waitcnt vmcnt(8)
	ds_write_b128 v92, v[208:211] offset:13824
	s_waitcnt lgkmcnt(12)
	v_mfma_f32_32x32x16_bf16 v[32:47], v[220:223], v[130:133], v[32:47]
	ds_read_b128 v[106:109], v91 offset:18496
	ds_read_b128 v[110:113], v90 offset:64
	ds_read_b128 v[114:117], v90 offset:96
	ds_read_b128 v[130:133], v91 offset:18528
	ds_read_b128 v[134:137], v91 offset:23104
	ds_read_b128 v[142:145], v91 offset:23136
	v_mfma_f32_32x32x16_bf16 v[16:31], v[216:219], v[212:215], v[16:31]
	v_mfma_f32_32x32x16_bf16 v[0:15], v[220:223], v[212:215], v[0:15]
	s_waitcnt lgkmcnt(14)
	v_mfma_f32_32x32x16_bf16 v[48:63], v[232:235], v[224:227], v[48:63]
	v_mfma_f32_32x32x16_bf16 v[32:47], v[236:239], v[224:227], v[32:47]
	v_mfma_f32_32x32x16_bf16 v[16:31], v[232:235], v[228:231], v[16:31]
	v_mfma_f32_32x32x16_bf16 v[0:15], v[236:239], v[228:231], v[0:15]
	s_waitcnt lgkmcnt(4)
	v_mfma_f32_32x32x16_bf16 v[48:63], v[106:109], v[110:113], v[48:63]
	s_waitcnt lgkmcnt(1)
	v_mfma_f32_32x32x16_bf16 v[32:47], v[134:137], v[110:113], v[32:47]
	ds_read_b128 v[110:113], v90 offset:4672
	ds_read_b128 v[172:175], v90 offset:4704
	s_waitcnt lgkmcnt(1)
	v_mfma_f32_32x32x16_bf16 v[16:31], v[106:109], v[110:113], v[16:31]
	v_mfma_f32_32x32x16_bf16 v[0:15], v[134:137], v[110:113], v[0:15]
	global_load_dwordx4 v[106:109], v[72:73], off offset:1664
	global_load_dwordx4 v[110:113], v[70:71], off offset:1664
	global_load_dwordx4 v[134:137], v[74:75], off offset:1664
	global_load_dwordx4 v[176:179], v[76:77], off offset:1664
	global_load_dwordx4 v[196:199], v[78:79], off offset:1664
	global_load_dwordx4 v[200:203], v[80:81], off offset:1664
	v_mfma_f32_32x32x16_bf16 v[48:63], v[130:133], v[114:117], v[48:63]
	v_mfma_f32_32x32x16_bf16 v[32:47], v[142:145], v[114:117], v[32:47]
	global_load_dwordx4 v[114:117], v[82:83], off offset:1664
	global_load_dwordx4 v[208:211], v[84:85], off offset:1664
	s_waitcnt lgkmcnt(0)
	s_barrier
	v_mfma_f32_32x32x16_bf16 v[16:31], v[130:133], v[172:175], v[16:31]
	ds_read_b128 v[130:133], v88 offset:36864
	ds_read_b128 v[212:215], v88 offset:41472
	ds_read_b128 v[216:219], v89 offset:55296
	ds_read_b128 v[220:223], v89 offset:59904
	ds_read_b128 v[224:227], v90 offset:36896
	ds_read_b128 v[228:231], v90 offset:41504
	ds_read_b128 v[232:235], v91 offset:55328
	ds_read_b128 v[236:239], v91 offset:59936
	v_mfma_f32_32x32x16_bf16 v[0:15], v[142:145], v[172:175], v[0:15]
	s_waitcnt lgkmcnt(5)
	v_mfma_f32_32x32x16_bf16 v[48:63], v[216:219], v[130:133], v[48:63]
	s_waitcnt vmcnt(15)
	ds_write_b128 v87, v[118:121]
	s_waitcnt vmcnt(14)
	ds_write_b128 v87, v[122:125] offset:18432
	s_waitcnt vmcnt(13)
	ds_write_b128 v87, v[138:141] offset:4608
	s_waitcnt vmcnt(12)
	ds_write_b128 v87, v[180:183] offset:23040
	s_waitcnt vmcnt(11)
	ds_write_b128 v87, v[184:187] offset:9216
	s_waitcnt vmcnt(10)
	ds_write_b128 v87, v[188:191] offset:27648
	s_waitcnt vmcnt(9)
	ds_write_b128 v87, v[126:129] offset:13824
	s_waitcnt vmcnt(8)
	ds_write_b128 v87, v[192:195] offset:32256
	s_waitcnt lgkmcnt(12)
	v_mfma_f32_32x32x16_bf16 v[32:47], v[220:223], v[130:133], v[32:47]
	ds_read_b128 v[118:121], v91 offset:55360
	ds_read_b128 v[122:125], v90 offset:36928
	ds_read_b128 v[126:129], v90 offset:36960
	ds_read_b128 v[130:133], v91 offset:55392
	ds_read_b128 v[138:141], v91 offset:59968
	ds_read_b128 v[142:145], v91 offset:60000
	v_mfma_f32_32x32x16_bf16 v[16:31], v[216:219], v[212:215], v[16:31]
	v_mfma_f32_32x32x16_bf16 v[0:15], v[220:223], v[212:215], v[0:15]
	s_waitcnt lgkmcnt(14)
	v_mfma_f32_32x32x16_bf16 v[48:63], v[232:235], v[224:227], v[48:63]
	v_mfma_f32_32x32x16_bf16 v[32:47], v[236:239], v[224:227], v[32:47]
	v_mfma_f32_32x32x16_bf16 v[16:31], v[232:235], v[228:231], v[16:31]
	v_mfma_f32_32x32x16_bf16 v[0:15], v[236:239], v[228:231], v[0:15]
	s_waitcnt lgkmcnt(4)
	v_mfma_f32_32x32x16_bf16 v[48:63], v[118:121], v[122:125], v[48:63]
	s_waitcnt lgkmcnt(1)
	v_mfma_f32_32x32x16_bf16 v[32:47], v[138:141], v[122:125], v[32:47]
	ds_read_b128 v[122:125], v90 offset:41536
	ds_read_b128 v[172:175], v90 offset:41568
	s_waitcnt lgkmcnt(1)
	v_mfma_f32_32x32x16_bf16 v[16:31], v[118:121], v[122:125], v[16:31]
	v_mfma_f32_32x32x16_bf16 v[0:15], v[138:141], v[122:125], v[0:15]
	global_load_dwordx4 v[118:121], v[72:73], off offset:1792
	global_load_dwordx4 v[122:125], v[70:71], off offset:1792
	global_load_dwordx4 v[138:141], v[74:75], off offset:1792
	global_load_dwordx4 v[180:183], v[76:77], off offset:1792
	global_load_dwordx4 v[184:187], v[78:79], off offset:1792
	global_load_dwordx4 v[188:191], v[80:81], off offset:1792
	v_mfma_f32_32x32x16_bf16 v[48:63], v[130:133], v[126:129], v[48:63]
	v_mfma_f32_32x32x16_bf16 v[32:47], v[142:145], v[126:129], v[32:47]
	global_load_dwordx4 v[126:129], v[82:83], off offset:1792
	global_load_dwordx4 v[192:195], v[84:85], off offset:1792
	s_waitcnt lgkmcnt(0)
	s_barrier
	v_mfma_f32_32x32x16_bf16 v[16:31], v[130:133], v[172:175], v[16:31]
	ds_read_b128 v[130:133], v88
	ds_read_b128 v[212:215], v88 offset:4608
	ds_read_b128 v[216:219], v89 offset:18432
	ds_read_b128 v[220:223], v89 offset:23040
	ds_read_b128 v[224:227], v90 offset:32
	ds_read_b128 v[228:231], v90 offset:4640
	ds_read_b128 v[232:235], v91 offset:18464
	ds_read_b128 v[236:239], v91 offset:23072
	v_mfma_f32_32x32x16_bf16 v[0:15], v[142:145], v[172:175], v[0:15]
	s_waitcnt lgkmcnt(5)
	v_mfma_f32_32x32x16_bf16 v[48:63], v[216:219], v[130:133], v[48:63]
	s_waitcnt vmcnt(15)
	ds_write_b128 v87, v[106:109] offset:36864
	s_waitcnt vmcnt(14)
	ds_write_b128 v87, v[110:113] offset:55296
	s_waitcnt vmcnt(13)
	ds_write_b128 v87, v[134:137] offset:41472
	s_waitcnt vmcnt(12)
	ds_write_b128 v87, v[176:179] offset:59904
	s_waitcnt vmcnt(11)
	ds_write_b128 v87, v[196:199] offset:46080
	s_waitcnt vmcnt(10)
	ds_write_b128 v87, v[200:203] offset:64512
	s_waitcnt vmcnt(9)
	ds_write_b128 v87, v[114:117] offset:50688
	s_waitcnt vmcnt(8)
	ds_write_b128 v92, v[208:211] offset:13824
	s_waitcnt lgkmcnt(12)
	v_mfma_f32_32x32x16_bf16 v[32:47], v[220:223], v[130:133], v[32:47]
	ds_read_b128 v[106:109], v91 offset:18496
	ds_read_b128 v[110:113], v90 offset:64
	ds_read_b128 v[114:117], v90 offset:96
	ds_read_b128 v[130:133], v91 offset:18528
	ds_read_b128 v[134:137], v91 offset:23104
	ds_read_b128 v[142:145], v91 offset:23136
	v_mfma_f32_32x32x16_bf16 v[16:31], v[216:219], v[212:215], v[16:31]
	v_mfma_f32_32x32x16_bf16 v[0:15], v[220:223], v[212:215], v[0:15]
	s_waitcnt lgkmcnt(14)
	v_mfma_f32_32x32x16_bf16 v[48:63], v[232:235], v[224:227], v[48:63]
	v_mfma_f32_32x32x16_bf16 v[32:47], v[236:239], v[224:227], v[32:47]
	v_mfma_f32_32x32x16_bf16 v[16:31], v[232:235], v[228:231], v[16:31]
	v_mfma_f32_32x32x16_bf16 v[0:15], v[236:239], v[228:231], v[0:15]
	s_waitcnt lgkmcnt(4)
	v_mfma_f32_32x32x16_bf16 v[48:63], v[106:109], v[110:113], v[48:63]
	s_waitcnt lgkmcnt(1)
	v_mfma_f32_32x32x16_bf16 v[32:47], v[134:137], v[110:113], v[32:47]
	ds_read_b128 v[110:113], v90 offset:4672
	ds_read_b128 v[172:175], v90 offset:4704
	s_waitcnt lgkmcnt(1)
	v_mfma_f32_32x32x16_bf16 v[16:31], v[106:109], v[110:113], v[16:31]
	v_mfma_f32_32x32x16_bf16 v[0:15], v[134:137], v[110:113], v[0:15]
	global_load_dwordx4 v[106:109], v[72:73], off offset:1920
	s_nop 0
	global_load_dwordx4 v[70:73], v[70:71], off offset:1920
	s_nop 0
	global_load_dwordx4 v[110:113], v[74:75], off offset:1920
	s_nop 0
	global_load_dwordx4 v[74:77], v[76:77], off offset:1920
	s_nop 0
	global_load_dwordx4 v[134:137], v[78:79], off offset:1920
	s_nop 0
	global_load_dwordx4 v[78:81], v[80:81], off offset:1920
	v_mfma_f32_32x32x16_bf16 v[48:63], v[130:133], v[114:117], v[48:63]
	v_mfma_f32_32x32x16_bf16 v[32:47], v[142:145], v[114:117], v[32:47]
	global_load_dwordx4 v[114:117], v[82:83], off offset:1920
	s_nop 0
	global_load_dwordx4 v[82:85], v[84:85], off offset:1920
	s_waitcnt lgkmcnt(0)
	s_barrier
	v_mfma_f32_32x32x16_bf16 v[16:31], v[130:133], v[172:175], v[16:31]
	ds_read_b128 v[130:133], v88 offset:36864
	ds_read_b128 v[176:179], v88 offset:41472
	ds_read_b128 v[196:199], v89 offset:55296
	ds_read_b128 v[200:203], v89 offset:59904
	ds_read_b128 v[208:211], v90 offset:36896
	ds_read_b128 v[212:215], v90 offset:41504
	ds_read_b128 v[216:219], v91 offset:55328
	ds_read_b128 v[220:223], v91 offset:59936
	v_mfma_f32_32x32x16_bf16 v[0:15], v[142:145], v[172:175], v[0:15]
	s_waitcnt lgkmcnt(5)
	v_mfma_f32_32x32x16_bf16 v[48:63], v[196:199], v[130:133], v[48:63]
	s_waitcnt vmcnt(15)
	ds_write_b128 v87, v[118:121]
	s_waitcnt vmcnt(14)
	ds_write_b128 v87, v[122:125] offset:18432
	s_waitcnt vmcnt(13)
	ds_write_b128 v87, v[138:141] offset:4608
	s_waitcnt vmcnt(12)
	ds_write_b128 v87, v[180:183] offset:23040
	s_waitcnt vmcnt(11)
	ds_write_b128 v87, v[184:187] offset:9216
	s_waitcnt vmcnt(10)
	ds_write_b128 v87, v[188:191] offset:27648
	s_waitcnt vmcnt(9)
	ds_write_b128 v87, v[126:129] offset:13824
	s_waitcnt vmcnt(8)
	ds_write_b128 v87, v[192:195] offset:32256
	s_waitcnt lgkmcnt(12)
	v_mfma_f32_32x32x16_bf16 v[32:47], v[200:203], v[130:133], v[32:47]
	ds_read_b128 v[118:121], v91 offset:55360
	ds_read_b128 v[122:125], v90 offset:36928
	ds_read_b128 v[126:129], v90 offset:36960
	ds_read_b128 v[130:133], v91 offset:55392
	ds_read_b128 v[138:141], v91 offset:59968
	ds_read_b128 v[142:145], v91 offset:60000
	v_mfma_f32_32x32x16_bf16 v[16:31], v[196:199], v[176:179], v[16:31]
	v_mfma_f32_32x32x16_bf16 v[0:15], v[200:203], v[176:179], v[0:15]
	s_waitcnt lgkmcnt(14)
	v_mfma_f32_32x32x16_bf16 v[48:63], v[216:219], v[208:211], v[48:63]
	v_mfma_f32_32x32x16_bf16 v[32:47], v[220:223], v[208:211], v[32:47]
	v_mfma_f32_32x32x16_bf16 v[16:31], v[216:219], v[212:215], v[16:31]
	v_mfma_f32_32x32x16_bf16 v[0:15], v[220:223], v[212:215], v[0:15]
	s_waitcnt lgkmcnt(4)
	v_mfma_f32_32x32x16_bf16 v[48:63], v[118:121], v[122:125], v[48:63]
	s_waitcnt lgkmcnt(1)
	v_mfma_f32_32x32x16_bf16 v[32:47], v[138:141], v[122:125], v[32:47]
	ds_read_b128 v[122:125], v90 offset:41536
	ds_read_b128 v[172:175], v90 offset:41568
	s_waitcnt lgkmcnt(0)
	s_barrier
	v_mfma_f32_32x32x16_bf16 v[16:31], v[118:121], v[122:125], v[16:31]
	v_mfma_f32_32x32x16_bf16 v[0:15], v[138:141], v[122:125], v[0:15]
	v_mfma_f32_32x32x16_bf16 v[48:63], v[130:133], v[126:129], v[48:63]
	v_mfma_f32_32x32x16_bf16 v[32:47], v[142:145], v[126:129], v[32:47]
	v_mfma_f32_32x32x16_bf16 v[16:31], v[130:133], v[172:175], v[16:31]
	ds_read_b128 v[118:121], v88
	ds_read_b128 v[122:125], v88 offset:4608
	ds_read_b128 v[126:129], v89 offset:18432
	ds_read_b128 v[130:133], v89 offset:23040
	ds_read_b128 v[138:141], v90 offset:32
	ds_read_b128 v[176:179], v90 offset:4640
	ds_read_b128 v[180:183], v91 offset:18464
	ds_read_b128 v[184:187], v91 offset:23072
	v_mfma_f32_32x32x16_bf16 v[0:15], v[142:145], v[172:175], v[0:15]
	s_waitcnt lgkmcnt(5)
	v_mfma_f32_32x32x16_bf16 v[48:63], v[126:129], v[118:121], v[48:63]
	s_waitcnt vmcnt(7)
	ds_write_b128 v87, v[106:109] offset:36864
	s_waitcnt vmcnt(6)
	ds_write_b128 v87, v[70:73] offset:55296
	s_waitcnt vmcnt(5)
	ds_write_b128 v87, v[110:113] offset:41472
	s_waitcnt vmcnt(4)
	ds_write_b128 v87, v[74:77] offset:59904
	s_waitcnt vmcnt(3)
	ds_write_b128 v87, v[134:137] offset:46080
	s_waitcnt vmcnt(2)
	ds_write_b128 v87, v[78:81] offset:64512
	s_waitcnt vmcnt(1)
	ds_write_b128 v87, v[114:117] offset:50688
	s_waitcnt vmcnt(0)
	ds_write_b128 v92, v[82:85] offset:13824
	ds_read_b128 v[70:73], v91 offset:18496
	ds_read_b128 v[74:77], v90 offset:64
	ds_read_b128 v[78:81], v90 offset:96
	ds_read_b128 v[82:85], v91 offset:18528
	ds_read_b128 v[106:109], v91 offset:23104
	ds_read_b128 v[110:113], v91 offset:23136
	s_waitcnt lgkmcnt(14)
	v_mfma_f32_32x32x16_bf16 v[32:47], v[130:133], v[118:121], v[32:47]
	v_mfma_f32_32x32x16_bf16 v[16:31], v[126:129], v[122:125], v[16:31]
	v_mfma_f32_32x32x16_bf16 v[0:15], v[130:133], v[122:125], v[0:15]
	v_mfma_f32_32x32x16_bf16 v[48:63], v[180:183], v[138:141], v[48:63]
	v_mfma_f32_32x32x16_bf16 v[32:47], v[184:187], v[138:141], v[32:47]
	v_mfma_f32_32x32x16_bf16 v[16:31], v[180:183], v[176:179], v[16:31]
	v_mfma_f32_32x32x16_bf16 v[0:15], v[184:187], v[176:179], v[0:15]
	s_waitcnt lgkmcnt(4)
	v_mfma_f32_32x32x16_bf16 v[48:63], v[70:73], v[74:77], v[48:63]
	s_waitcnt lgkmcnt(1)
	v_mfma_f32_32x32x16_bf16 v[32:47], v[106:109], v[74:77], v[32:47]
	ds_read_b128 v[74:77], v90 offset:4672
	ds_read_b128 v[114:117], v90 offset:4704
	s_waitcnt lgkmcnt(0)
	s_barrier
	v_mfma_f32_32x32x16_bf16 v[16:31], v[70:73], v[74:77], v[16:31]
	v_mfma_f32_32x32x16_bf16 v[0:15], v[106:109], v[74:77], v[0:15]
	v_mfma_f32_32x32x16_bf16 v[48:63], v[82:85], v[78:81], v[48:63]
	v_mfma_f32_32x32x16_bf16 v[32:47], v[110:113], v[78:81], v[32:47]
	v_mfma_f32_32x32x16_bf16 v[16:31], v[82:85], v[114:117], v[16:31]
	ds_read_b128 v[70:73], v88 offset:36864
	ds_read_b128 v[74:77], v88 offset:41472
	ds_read_b128 v[78:81], v89 offset:55296
	ds_read_b128 v[82:85], v89 offset:59904
	ds_read_b128 v[106:109], v90 offset:36896
	ds_read_b128 v[118:121], v90 offset:41504
	ds_read_b128 v[122:125], v91 offset:55328
	ds_read_b128 v[126:129], v91 offset:59936
	v_mfma_f32_32x32x16_bf16 v[0:15], v[110:113], v[114:117], v[0:15]
	s_waitcnt lgkmcnt(5)
	v_mfma_f32_32x32x16_bf16 v[48:63], v[78:81], v[70:73], v[48:63]
	s_waitcnt lgkmcnt(4)
	v_mfma_f32_32x32x16_bf16 v[32:47], v[82:85], v[70:73], v[32:47]
	v_mfma_f32_32x32x16_bf16 v[0:15], v[82:85], v[74:77], v[0:15]
	v_mfma_f32_32x32x16_bf16 v[16:31], v[78:81], v[74:77], v[16:31]
	ds_read_b128 v[70:73], v91 offset:55360
	ds_read_b128 v[74:77], v90 offset:36928
	ds_read_b128 v[78:81], v90 offset:36960
	ds_read_b128 v[82:85], v91 offset:55392
	s_waitcnt lgkmcnt(5)
	v_mfma_f32_32x32x16_bf16 v[48:63], v[122:125], v[106:109], v[48:63]
	s_waitcnt lgkmcnt(4)
	v_mfma_f32_32x32x16_bf16 v[32:47], v[126:129], v[106:109], v[32:47]
	ds_read_b128 v[106:109], v91 offset:59968
	ds_read_b128 v[110:113], v91 offset:60000
	v_mfma_f32_32x32x16_bf16 v[0:15], v[126:129], v[118:121], v[0:15]
	v_mfma_f32_32x32x16_bf16 v[16:31], v[122:125], v[118:121], v[16:31]
	s_waitcnt lgkmcnt(4)
	v_mfma_f32_32x32x16_bf16 v[48:63], v[70:73], v[74:77], v[48:63]
	s_waitcnt lgkmcnt(1)
	v_mfma_f32_32x32x16_bf16 v[32:47], v[106:109], v[74:77], v[32:47]
	ds_read_b128 v[74:77], v90 offset:41536
	ds_read_b128 v[114:117], v90 offset:41568
	s_waitcnt lgkmcnt(0)
	s_barrier
	s_barrier
	v_mfma_f32_32x32x16_bf16 v[0:15], v[106:109], v[74:77], v[0:15]
	v_mfma_f32_32x32x16_bf16 v[16:31], v[70:73], v[74:77], v[16:31]
	v_mfma_f32_32x32x16_bf16 v[48:63], v[82:85], v[78:81], v[48:63]
	v_mfma_f32_32x32x16_bf16 v[32:47], v[110:113], v[78:81], v[32:47]
	s_nop 10
	ds_write_b128 v93, v[48:51]
	ds_write_b128 v93, v[52:55] offset:32
	ds_write_b128 v93, v[56:59] offset:64
	ds_write_b128 v93, v[60:63] offset:96
	ds_write_b128 v93, v[32:35] offset:128
	v_mfma_f32_32x32x16_bf16 v[0:15], v[110:113], v[114:117], v[0:15]
	v_mfma_f32_32x32x16_bf16 v[16:31], v[82:85], v[114:117], v[16:31]
	ds_write_b128 v93, v[36:39] offset:160
	ds_write_b128 v93, v[40:43] offset:192
	ds_write_b128 v93, v[44:47] offset:224
	s_nop 8
	ds_write_b128 v93, v[16:19] offset:16896
	ds_write_b128 v93, v[20:23] offset:16928
	ds_write_b128 v93, v[24:27] offset:16960
	ds_write_b128 v93, v[28:31] offset:16992
	ds_write_b128 v93, v[0:3] offset:17024
	ds_write_b128 v93, v[4:7] offset:17056
	ds_write_b128 v93, v[8:11] offset:17088
	ds_write_b128 v93, v[12:15] offset:17120
	v_or_b32_e32 v12, s15, v86
	v_readlane_b32 s48, v253, 0
	v_readlane_b32 s49, v253, 1
	v_readlane_b32 s50, v253, 2
	v_readlane_b32 s51, v253, 3
	v_readlane_b32 s52, v253, 4
	v_readlane_b32 s53, v253, 5
	v_readlane_b32 s54, v253, 6
	v_readlane_b32 s55, v253, 7
	v_readlane_b32 s56, v253, 8
	v_readlane_b32 s57, v253, 9
	v_readlane_b32 s58, v253, 10
	v_readlane_b32 s59, v253, 11
	v_readlane_b32 s60, v253, 12
	v_readlane_b32 s61, v253, 13
	v_readlane_b32 s62, v253, 14
	v_readlane_b32 s63, v253, 15
	s_lshl_b32 s14, s14, 10
	s_or_b32 s14, s14, s22
	v_add_u32_e32 v18, s14, v165
	v_lshlrev_b32_e32 v18, 12, v18
	v_lshl_add_u32 v18, v12, 2, v18
	s_cmp_ge_u32 s14, 0x10000
	s_cselect_b32 s20, s50, s48
	s_cselect_b32 s21, s51, s49
	s_cselect_b32 s22, 0x10000000, 0
	v_subrev_u32_e32 v64, s22, v18
	global_load_dwordx4 v[32:35], v64, s[20:21]
	v_add_u32_e32 v64, 0x8000, v64
	global_load_dwordx4 v[36:39], v64, s[20:21]
	v_add_u32_e32 v64, 0x8000, v64
	global_load_dwordx4 v[40:43], v64, s[20:21]
	v_add_u32_e32 v64, 0x8000, v64
	global_load_dwordx4 v[44:47], v64, s[20:21]
	v_add_u32_e32 v64, 0x8000, v64
	global_load_dwordx4 v[48:51], v64, s[20:21]
	v_add_u32_e32 v64, 0x8000, v64
	global_load_dwordx4 v[52:55], v64, s[20:21]
	v_add_u32_e32 v64, 0x8000, v64
	global_load_dwordx4 v[56:59], v64, s[20:21]
	v_add_u32_e32 v64, 0x8000, v64
	global_load_dwordx4 v[60:63], v64, s[20:21]
	v_add_u32_e32 v64, 0x8000, v64
	s_waitcnt lgkmcnt(0)
	s_barrier
	ds_read_b128 v[2:5], v104
	ds_read_b128 v[6:9], v104 offset:4224
	ds_read_b128 v[10:13], v104 offset:8448
	ds_read_b128 v[14:17], v104 offset:12672
	s_waitcnt vmcnt(7) lgkmcnt(3)
	v_pk_add_f32 v[32:33], v[2:3], v[32:33]
	v_pk_add_f32 v[34:35], v[4:5], v[34:35]
	global_store_dwordx4 v18, v[32:35], s[92:93]
	v_add_u32_e32 v18, 0x8000, v18
	global_load_dwordx4 v[32:35], v64, s[20:21]
	v_add_u32_e32 v64, 0x8000, v64
	ds_read_b128 v[2:5], v104 offset:16896
	s_waitcnt vmcnt(8) lgkmcnt(3)
	v_pk_add_f32 v[36:37], v[6:7], v[36:37]
	v_pk_add_f32 v[38:39], v[8:9], v[38:39]
	global_store_dwordx4 v18, v[36:39], s[92:93]
	v_add_u32_e32 v18, 0x8000, v18
	global_load_dwordx4 v[36:39], v64, s[20:21]
	v_add_u32_e32 v64, 0x8000, v64
	ds_read_b128 v[6:9], v104 offset:21120
	s_waitcnt vmcnt(9) lgkmcnt(3)
	v_pk_add_f32 v[40:41], v[10:11], v[40:41]
	v_pk_add_f32 v[42:43], v[12:13], v[42:43]
	global_store_dwordx4 v18, v[40:43], s[92:93]
	v_add_u32_e32 v18, 0x8000, v18
	global_load_dwordx4 v[40:43], v64, s[20:21]
	v_add_u32_e32 v64, 0x8000, v64
	ds_read_b128 v[10:13], v104 offset:25344
	s_waitcnt vmcnt(10) lgkmcnt(3)
	v_pk_add_f32 v[44:45], v[14:15], v[44:45]
	v_pk_add_f32 v[46:47], v[16:17], v[46:47]
	global_store_dwordx4 v18, v[44:47], s[92:93]
	v_add_u32_e32 v18, 0x8000, v18
	global_load_dwordx4 v[44:47], v64, s[20:21]
	v_add_u32_e32 v64, 0x8000, v64
	ds_read_b128 v[14:17], v104 offset:29568
	s_waitcnt vmcnt(11) lgkmcnt(3)
	v_pk_add_f32 v[48:49], v[2:3], v[48:49]
	v_pk_add_f32 v[50:51], v[4:5], v[50:51]
	global_store_dwordx4 v18, v[48:51], s[92:93]
	v_add_u32_e32 v18, 0x8000, v18
	global_load_dwordx4 v[48:51], v64, s[20:21]
	v_add_u32_e32 v64, 0x8000, v64
	ds_read_b128 v[2:5], v104 offset:33792
	s_waitcnt vmcnt(12) lgkmcnt(3)
	v_pk_add_f32 v[52:53], v[6:7], v[52:53]
	v_pk_add_f32 v[54:55], v[8:9], v[54:55]
	global_store_dwordx4 v18, v[52:55], s[92:93]
	v_add_u32_e32 v18, 0x8000, v18
	global_load_dwordx4 v[52:55], v64, s[20:21]
	v_add_u32_e32 v64, 0x8000, v64
	ds_read_b128 v[6:9], v104 offset:38016
	s_waitcnt vmcnt(13) lgkmcnt(3)
	v_pk_add_f32 v[56:57], v[10:11], v[56:57]
	v_pk_add_f32 v[58:59], v[12:13], v[58:59]
	global_store_dwordx4 v18, v[56:59], s[92:93]
	v_add_u32_e32 v18, 0x8000, v18
	global_load_dwordx4 v[56:59], v64, s[20:21]
	v_add_u32_e32 v64, 0x8000, v64
	ds_read_b128 v[10:13], v104 offset:42240
	s_waitcnt vmcnt(14) lgkmcnt(3)
	v_pk_add_f32 v[60:61], v[14:15], v[60:61]
	v_pk_add_f32 v[62:63], v[16:17], v[62:63]
	global_store_dwordx4 v18, v[60:63], s[92:93]
	v_add_u32_e32 v18, 0x8000, v18
	global_load_dwordx4 v[60:63], v64, s[20:21]
	ds_read_b128 v[14:17], v104 offset:46464
	s_waitcnt vmcnt(14) lgkmcnt(3)
	v_pk_add_f32 v[32:33], v[2:3], v[32:33]
	v_pk_add_f32 v[34:35], v[4:5], v[34:35]
	global_store_dwordx4 v18, v[32:35], s[92:93]
	v_add_u32_e32 v18, 0x8000, v18
	ds_read_b128 v[2:5], v104 offset:50688
	s_waitcnt vmcnt(13) lgkmcnt(3)
	v_pk_add_f32 v[36:37], v[6:7], v[36:37]
	v_pk_add_f32 v[38:39], v[8:9], v[38:39]
	global_store_dwordx4 v18, v[36:39], s[92:93]
	v_add_u32_e32 v18, 0x8000, v18
	ds_read_b128 v[6:9], v104 offset:54912
	s_waitcnt vmcnt(12) lgkmcnt(3)
	v_pk_add_f32 v[40:41], v[10:11], v[40:41]
	v_pk_add_f32 v[42:43], v[12:13], v[42:43]
	global_store_dwordx4 v18, v[40:43], s[92:93]
	v_add_u32_e32 v18, 0x8000, v18
	ds_read_b128 v[10:13], v104 offset:59136
	s_waitcnt vmcnt(11) lgkmcnt(3)
	v_pk_add_f32 v[44:45], v[14:15], v[44:45]
	v_pk_add_f32 v[46:47], v[16:17], v[46:47]
	global_store_dwordx4 v18, v[44:47], s[92:93]
	v_add_u32_e32 v18, 0x8000, v18
	ds_read_b128 v[14:17], v104 offset:63360
	s_waitcnt vmcnt(10) lgkmcnt(3)
	v_pk_add_f32 v[48:49], v[2:3], v[48:49]
	v_pk_add_f32 v[50:51], v[4:5], v[50:51]
	global_store_dwordx4 v18, v[48:51], s[92:93]
	v_add_u32_e32 v18, 0x8000, v18
	s_waitcnt vmcnt(9) lgkmcnt(2)
	v_pk_add_f32 v[52:53], v[6:7], v[52:53]
	v_pk_add_f32 v[54:55], v[8:9], v[54:55]
	global_store_dwordx4 v18, v[52:55], s[92:93]
	v_add_u32_e32 v18, 0x8000, v18
	s_waitcnt vmcnt(8) lgkmcnt(1)
	v_pk_add_f32 v[56:57], v[10:11], v[56:57]
	v_pk_add_f32 v[58:59], v[12:13], v[58:59]
	global_store_dwordx4 v18, v[56:59], s[92:93]
	v_add_u32_e32 v18, 0x8000, v18
	s_waitcnt vmcnt(7) lgkmcnt(0)
	v_pk_add_f32 v[60:61], v[14:15], v[60:61]
	v_pk_add_f32 v[62:63], v[16:17], v[62:63]
	global_store_dwordx4 v18, v[60:63], s[92:93]
	s_branch .LBB0_570

.LBB0_1049:
	s_lshl_b32 s16, s16, 3
	s_and_b32 s18, s8, 7
	s_or_b32 s16, s18, s16
	s_cmpk_gt_u32 s16, 0x203
	s_cbranch_scc1 .LBB0_1048
	s_lshl_b32 s17, s17, 7
	s_and_b32 s18, s17, 0x380
	s_lshl_b32 s16, s16, 7
	v_or_b32_e32 v0, s18, v157
	v_lshlrev_b32_e32 v64, 11, v0
	v_or_b32_e32 v0, s16, v157
	v_lshl_add_u64 v[78:79], v[66:67], 0, v[64:65]
	v_lshlrev_b32_e32 v64, 11, v0
	v_lshl_add_u64 v[80:81], v[68:69], 0, v[64:65]
	v_add_co_u32_e32 v82, vcc, 0x10000, v80
	global_load_dwordx4 v[0:3], v[80:81], off
	global_load_dwordx4 v[4:7], v[78:79], off
	v_addc_co_u32_e32 v83, vcc, 0, v81, vcc
	v_add_co_u32_e32 v84, vcc, 0x10000, v78
	global_load_dwordx4 v[8:11], v[82:83], off
	s_nop 0
	v_addc_co_u32_e32 v85, vcc, 0, v79, vcc
	v_add_co_u32_e32 v86, vcc, 0x20000, v80
	global_load_dwordx4 v[12:15], v[84:85], off
	s_nop 0
	v_addc_co_u32_e32 v87, vcc, 0, v81, vcc
	v_add_co_u32_e32 v88, vcc, 0x20000, v78
	global_load_dwordx4 v[16:19], v[86:87], off
	s_nop 0
	v_addc_co_u32_e32 v89, vcc, 0, v79, vcc
	v_add_co_u32_e32 v90, vcc, 0x30000, v80
	v_lshl_add_u64 v[32:33], v[80:81], 0, s[2:3]
	s_nop 0
	v_addc_co_u32_e32 v91, vcc, 0, v81, vcc
	v_add_co_u32_e32 v92, vcc, 0x30000, v78
	v_lshl_add_u64 v[34:35], v[80:81], 0, s[4:5]
	s_nop 0
	v_addc_co_u32_e32 v93, vcc, 0, v79, vcc
	global_load_dwordx4 v[20:23], v[88:89], off
	v_lshl_add_u64 v[36:37], v[80:81], 0, s[6:7]
	global_load_dwordx4 v[24:27], v[90:91], off
	global_load_dwordx4 v[28:31], v[92:93], off
	global_load_dwordx4 v[102:105], v[80:81], off offset:128
	global_load_dwordx4 v[106:109], v[78:79], off offset:128
	global_load_dwordx4 v[110:113], v[32:33], off offset:128
	global_load_dwordx4 v[114:117], v[84:85], off offset:128
	global_load_dwordx4 v[118:121], v[34:35], off offset:128
	global_load_dwordx4 v[122:125], v[88:89], off offset:128
	global_load_dwordx4 v[126:129], v[36:37], off offset:128
	global_load_dwordx4 v[130:133], v[92:93], off offset:128
	s_barrier
	global_load_dwordx4 v[134:137], v[80:81], off offset:256
	global_load_dwordx4 v[138:141], v[78:79], off offset:256
	global_load_dwordx4 v[142:145], v[32:33], off offset:256
	global_load_dwordx4 v[146:149], v[84:85], off offset:256
	global_load_dwordx4 v[186:189], v[34:35], off offset:256
	global_load_dwordx4 v[190:193], v[88:89], off offset:256
	global_load_dwordx4 v[194:197], v[36:37], off offset:256
	global_load_dwordx4 v[198:201], v[92:93], off offset:256
	s_mov_b32 s17, 0
	s_waitcnt vmcnt(22)
	ds_write_b128 v95, v[4:7] offset:18432
	ds_write_b128 v95, v[0:3]
	s_waitcnt vmcnt(21)
	ds_write_b128 v95, v[8:11] offset:4608
	s_waitcnt vmcnt(20)
	ds_write_b128 v95, v[12:15] offset:23040
	s_waitcnt vmcnt(19)
	ds_write_b128 v95, v[16:19] offset:9216
	s_waitcnt vmcnt(18)
	ds_write_b128 v95, v[20:23] offset:27648
	s_waitcnt vmcnt(17)
	ds_write_b128 v95, v[24:27] offset:13824
	s_waitcnt vmcnt(16)
	ds_write_b128 v95, v[28:31] offset:32256
	s_waitcnt lgkmcnt(0)
	s_barrier
	ds_read_b128 v[0:3], v96
	ds_read_b128 v[4:7], v96 offset:4608
	ds_read_b128 v[8:11], v97 offset:18432
	ds_read_b128 v[12:15], v97 offset:23040
	ds_read_b128 v[212:215], v98 offset:32
	ds_read_b128 v[216:219], v98 offset:4640
	ds_read_b128 v[220:223], v99 offset:18464
	ds_read_b128 v[224:227], v99 offset:23072
	s_waitcnt lgkmcnt(5)
	v_mfma_f32_32x32x16_bf16 v[48:63], v[8:11], v[0:3], 0
	s_waitcnt vmcnt(15)
	ds_write_b128 v95, v[102:105] offset:36864
	s_waitcnt vmcnt(14)
	ds_write_b128 v95, v[106:109] offset:55296
	s_waitcnt vmcnt(13)
	ds_write_b128 v95, v[110:113] offset:41472
	s_waitcnt vmcnt(12)
	ds_write_b128 v95, v[114:117] offset:59904
	s_waitcnt vmcnt(11)
	ds_write_b128 v95, v[118:121] offset:46080
	s_waitcnt vmcnt(10)
	ds_write_b128 v95, v[122:125] offset:64512
	s_waitcnt vmcnt(9)
	ds_write_b128 v95, v[126:129] offset:50688
	s_waitcnt vmcnt(8)
	ds_write_b128 v100, v[130:133] offset:13824
	ds_read_b128 v[102:105], v99 offset:18496
	ds_read_b128 v[106:109], v98 offset:64
	ds_read_b128 v[110:113], v98 offset:96
	ds_read_b128 v[114:117], v99 offset:18528
	ds_read_b128 v[118:121], v99 offset:23104
	ds_read_b128 v[122:125], v99 offset:23136
	s_waitcnt lgkmcnt(14)
	v_mfma_f32_32x32x16_bf16 v[32:47], v[12:15], v[0:3], 0
	v_mfma_f32_32x32x16_bf16 v[16:31], v[8:11], v[4:7], 0
	v_mfma_f32_32x32x16_bf16 v[0:15], v[12:15], v[4:7], 0
	v_mfma_f32_32x32x16_bf16 v[48:63], v[220:223], v[212:215], v[48:63]
	v_mfma_f32_32x32x16_bf16 v[32:47], v[224:227], v[212:215], v[32:47]
	v_mfma_f32_32x32x16_bf16 v[16:31], v[220:223], v[216:219], v[16:31]
	v_mfma_f32_32x32x16_bf16 v[0:15], v[224:227], v[216:219], v[0:15]
	s_waitcnt lgkmcnt(4)
	v_mfma_f32_32x32x16_bf16 v[48:63], v[102:105], v[106:109], v[48:63]
	s_waitcnt lgkmcnt(1)
	v_mfma_f32_32x32x16_bf16 v[32:47], v[118:121], v[106:109], v[32:47]
	ds_read_b128 v[106:109], v98 offset:4672
	ds_read_b128 v[126:129], v98 offset:4704
	s_waitcnt lgkmcnt(1)
	v_mfma_f32_32x32x16_bf16 v[16:31], v[102:105], v[106:109], v[16:31]
	v_mfma_f32_32x32x16_bf16 v[0:15], v[118:121], v[106:109], v[0:15]
	global_load_dwordx4 v[102:105], v[80:81], off offset:384
	global_load_dwordx4 v[106:109], v[78:79], off offset:384
	global_load_dwordx4 v[118:121], v[82:83], off offset:384
	global_load_dwordx4 v[130:133], v[84:85], off offset:384
	global_load_dwordx4 v[212:215], v[86:87], off offset:384
	global_load_dwordx4 v[216:219], v[88:89], off offset:384
	v_mfma_f32_32x32x16_bf16 v[48:63], v[114:117], v[110:113], v[48:63]
	v_mfma_f32_32x32x16_bf16 v[32:47], v[122:125], v[110:113], v[32:47]
	global_load_dwordx4 v[110:113], v[90:91], off offset:384
	global_load_dwordx4 v[220:223], v[92:93], off offset:384
	s_waitcnt lgkmcnt(0)
	s_barrier
	v_mfma_f32_32x32x16_bf16 v[16:31], v[114:117], v[126:129], v[16:31]
	ds_read_b128 v[114:117], v96 offset:36864
	ds_read_b128 v[224:227], v96 offset:41472
	ds_read_b128 v[228:231], v97 offset:55296
	ds_read_b128 v[232:235], v97 offset:59904
	ds_read_b128 v[236:239], v98 offset:36896
	ds_read_b128 v[240:243], v98 offset:41504
	ds_read_b128 v[244:247], v99 offset:55328
	ds_read_b128 v[248:251], v99 offset:59936
	v_mfma_f32_32x32x16_bf16 v[0:15], v[122:125], v[126:129], v[0:15]
	s_waitcnt lgkmcnt(5)
	v_mfma_f32_32x32x16_bf16 v[48:63], v[228:231], v[114:117], v[48:63]
	s_waitcnt vmcnt(15)
	ds_write_b128 v95, v[134:137]
	s_waitcnt vmcnt(14)
	ds_write_b128 v95, v[138:141] offset:18432
	s_waitcnt vmcnt(13)
	ds_write_b128 v95, v[142:145] offset:4608
	s_waitcnt vmcnt(12)
	ds_write_b128 v95, v[146:149] offset:23040
	s_waitcnt vmcnt(11)
	ds_write_b128 v95, v[186:189] offset:9216
	s_waitcnt vmcnt(10)
	ds_write_b128 v95, v[190:193] offset:27648
	s_waitcnt vmcnt(9)
	ds_write_b128 v95, v[194:197] offset:13824
	s_waitcnt vmcnt(8)
	ds_write_b128 v95, v[198:201] offset:32256
	s_waitcnt lgkmcnt(12)
	v_mfma_f32_32x32x16_bf16 v[32:47], v[232:235], v[114:117], v[32:47]
	ds_read_b128 v[114:117], v99 offset:55360
	ds_read_b128 v[122:125], v98 offset:36928
	ds_read_b128 v[126:129], v98 offset:36960
	ds_read_b128 v[134:137], v99 offset:55392
	ds_read_b128 v[138:141], v99 offset:59968
	ds_read_b128 v[142:145], v99 offset:60000
	v_mfma_f32_32x32x16_bf16 v[16:31], v[228:231], v[224:227], v[16:31]
	v_mfma_f32_32x32x16_bf16 v[0:15], v[232:235], v[224:227], v[0:15]
	s_waitcnt lgkmcnt(14)
	v_mfma_f32_32x32x16_bf16 v[48:63], v[244:247], v[236:239], v[48:63]
	v_mfma_f32_32x32x16_bf16 v[32:47], v[248:251], v[236:239], v[32:47]
	v_mfma_f32_32x32x16_bf16 v[16:31], v[244:247], v[240:243], v[16:31]
	v_mfma_f32_32x32x16_bf16 v[0:15], v[248:251], v[240:243], v[0:15]
	s_waitcnt lgkmcnt(4)
	v_mfma_f32_32x32x16_bf16 v[48:63], v[114:117], v[122:125], v[48:63]
	s_waitcnt lgkmcnt(1)
	v_mfma_f32_32x32x16_bf16 v[32:47], v[138:141], v[122:125], v[32:47]
	ds_read_b128 v[122:125], v98 offset:41536
	ds_read_b128 v[146:149], v98 offset:41568
	s_waitcnt lgkmcnt(1)
	v_mfma_f32_32x32x16_bf16 v[16:31], v[114:117], v[122:125], v[16:31]
	v_mfma_f32_32x32x16_bf16 v[0:15], v[138:141], v[122:125], v[0:15]
	global_load_dwordx4 v[114:117], v[80:81], off offset:512
	global_load_dwordx4 v[122:125], v[78:79], off offset:512
	global_load_dwordx4 v[138:141], v[82:83], off offset:512
	global_load_dwordx4 v[186:189], v[84:85], off offset:512
	global_load_dwordx4 v[190:193], v[86:87], off offset:512
	global_load_dwordx4 v[194:197], v[88:89], off offset:512
	v_mfma_f32_32x32x16_bf16 v[48:63], v[134:137], v[126:129], v[48:63]
	v_mfma_f32_32x32x16_bf16 v[32:47], v[142:145], v[126:129], v[32:47]
	global_load_dwordx4 v[126:129], v[90:91], off offset:512
	global_load_dwordx4 v[198:201], v[92:93], off offset:512
	s_waitcnt lgkmcnt(0)
	s_barrier
	v_mfma_f32_32x32x16_bf16 v[16:31], v[134:137], v[146:149], v[16:31]
	ds_read_b128 v[134:137], v96
	ds_read_b128 v[224:227], v96 offset:4608
	ds_read_b128 v[228:231], v97 offset:18432
	ds_read_b128 v[232:235], v97 offset:23040
	ds_read_b128 v[236:239], v98 offset:32
	ds_read_b128 v[240:243], v98 offset:4640
	ds_read_b128 v[244:247], v99 offset:18464
	ds_read_b128 v[248:251], v99 offset:23072
	v_mfma_f32_32x32x16_bf16 v[0:15], v[142:145], v[146:149], v[0:15]
	s_waitcnt lgkmcnt(5)
	v_mfma_f32_32x32x16_bf16 v[48:63], v[228:231], v[134:137], v[48:63]
	s_waitcnt vmcnt(15)
	ds_write_b128 v95, v[102:105] offset:36864
	s_waitcnt vmcnt(14)
	ds_write_b128 v95, v[106:109] offset:55296
	s_waitcnt vmcnt(13)
	ds_write_b128 v95, v[118:121] offset:41472
	s_waitcnt vmcnt(12)
	ds_write_b128 v95, v[130:133] offset:59904
	s_waitcnt vmcnt(11)
	ds_write_b128 v95, v[212:215] offset:46080
	s_waitcnt vmcnt(10)
	ds_write_b128 v95, v[216:219] offset:64512
	s_waitcnt vmcnt(9)
	ds_write_b128 v95, v[110:113] offset:50688
	s_waitcnt vmcnt(8)
	ds_write_b128 v100, v[220:223] offset:13824
	ds_read_b128 v[102:105], v99 offset:18496
	ds_read_b128 v[106:109], v98 offset:64
	ds_read_b128 v[110:113], v98 offset:96
	ds_read_b128 v[118:121], v99 offset:18528
	s_waitcnt lgkmcnt(14)
	v_mfma_f32_32x32x16_bf16 v[32:47], v[232:235], v[134:137], v[32:47]
	ds_read_b128 v[130:133], v99 offset:23104
	ds_read_b128 v[134:137], v99 offset:23136
	v_mfma_f32_32x32x16_bf16 v[16:31], v[228:231], v[224:227], v[16:31]
	v_mfma_f32_32x32x16_bf16 v[0:15], v[232:235], v[224:227], v[0:15]
	s_waitcnt lgkmcnt(14)
	v_mfma_f32_32x32x16_bf16 v[48:63], v[244:247], v[236:239], v[48:63]
	v_mfma_f32_32x32x16_bf16 v[32:47], v[248:251], v[236:239], v[32:47]
	v_mfma_f32_32x32x16_bf16 v[16:31], v[244:247], v[240:243], v[16:31]
	v_mfma_f32_32x32x16_bf16 v[0:15], v[248:251], v[240:243], v[0:15]
	s_waitcnt lgkmcnt(4)
	v_mfma_f32_32x32x16_bf16 v[48:63], v[102:105], v[106:109], v[48:63]
	s_waitcnt lgkmcnt(1)
	v_mfma_f32_32x32x16_bf16 v[32:47], v[130:133], v[106:109], v[32:47]
	ds_read_b128 v[106:109], v98 offset:4672
	ds_read_b128 v[142:145], v98 offset:4704
	s_waitcnt lgkmcnt(1)
	v_mfma_f32_32x32x16_bf16 v[16:31], v[102:105], v[106:109], v[16:31]
	v_mfma_f32_32x32x16_bf16 v[0:15], v[130:133], v[106:109], v[0:15]
	global_load_dwordx4 v[102:105], v[80:81], off offset:640
	global_load_dwordx4 v[106:109], v[78:79], off offset:640
	global_load_dwordx4 v[130:133], v[82:83], off offset:640
	global_load_dwordx4 v[146:149], v[84:85], off offset:640
	global_load_dwordx4 v[212:215], v[86:87], off offset:640
	global_load_dwordx4 v[216:219], v[88:89], off offset:640
	v_mfma_f32_32x32x16_bf16 v[48:63], v[118:121], v[110:113], v[48:63]
	v_mfma_f32_32x32x16_bf16 v[32:47], v[134:137], v[110:113], v[32:47]
	global_load_dwordx4 v[110:113], v[90:91], off offset:640
	global_load_dwordx4 v[220:223], v[92:93], off offset:640
	s_waitcnt lgkmcnt(0)
	s_barrier
	v_mfma_f32_32x32x16_bf16 v[16:31], v[118:121], v[142:145], v[16:31]
	ds_read_b128 v[118:121], v96 offset:36864
	ds_read_b128 v[224:227], v96 offset:41472
	ds_read_b128 v[228:231], v97 offset:55296
	ds_read_b128 v[232:235], v97 offset:59904
	ds_read_b128 v[236:239], v98 offset:36896
	ds_read_b128 v[240:243], v98 offset:41504
	ds_read_b128 v[244:247], v99 offset:55328
	ds_read_b128 v[248:251], v99 offset:59936
	v_mfma_f32_32x32x16_bf16 v[0:15], v[134:137], v[142:145], v[0:15]
	s_waitcnt lgkmcnt(5)
	v_mfma_f32_32x32x16_bf16 v[48:63], v[228:231], v[118:121], v[48:63]
	s_waitcnt vmcnt(15)
	ds_write_b128 v95, v[114:117]
	s_waitcnt vmcnt(14)
	ds_write_b128 v95, v[122:125] offset:18432
	s_waitcnt vmcnt(13)
	ds_write_b128 v95, v[138:141] offset:4608
	s_waitcnt vmcnt(12)
	ds_write_b128 v95, v[186:189] offset:23040
	s_waitcnt vmcnt(11)
	ds_write_b128 v95, v[190:193] offset:9216
	s_waitcnt vmcnt(10)
	ds_write_b128 v95, v[194:197] offset:27648
	s_waitcnt vmcnt(9)
	ds_write_b128 v95, v[126:129] offset:13824
	s_waitcnt vmcnt(8)
	ds_write_b128 v95, v[198:201] offset:32256
	s_waitcnt lgkmcnt(12)
	v_mfma_f32_32x32x16_bf16 v[32:47], v[232:235], v[118:121], v[32:47]
	ds_read_b128 v[114:117], v99 offset:55360
	ds_read_b128 v[118:121], v98 offset:36928
	ds_read_b128 v[122:125], v98 offset:36960
	ds_read_b128 v[126:129], v99 offset:55392
	ds_read_b128 v[134:137], v99 offset:59968
	ds_read_b128 v[138:141], v99 offset:60000
	v_mfma_f32_32x32x16_bf16 v[16:31], v[228:231], v[224:227], v[16:31]
	v_mfma_f32_32x32x16_bf16 v[0:15], v[232:235], v[224:227], v[0:15]
	s_waitcnt lgkmcnt(14)
	v_mfma_f32_32x32x16_bf16 v[48:63], v[244:247], v[236:239], v[48:63]
	v_mfma_f32_32x32x16_bf16 v[32:47], v[248:251], v[236:239], v[32:47]
	v_mfma_f32_32x32x16_bf16 v[16:31], v[244:247], v[240:243], v[16:31]
	v_mfma_f32_32x32x16_bf16 v[0:15], v[248:251], v[240:243], v[0:15]
	s_waitcnt lgkmcnt(4)
	v_mfma_f32_32x32x16_bf16 v[48:63], v[114:117], v[118:121], v[48:63]
	s_waitcnt lgkmcnt(1)
	v_mfma_f32_32x32x16_bf16 v[32:47], v[134:137], v[118:121], v[32:47]
	ds_read_b128 v[118:121], v98 offset:41536
	ds_read_b128 v[142:145], v98 offset:41568
	s_waitcnt lgkmcnt(1)
	v_mfma_f32_32x32x16_bf16 v[16:31], v[114:117], v[118:121], v[16:31]
	v_mfma_f32_32x32x16_bf16 v[0:15], v[134:137], v[118:121], v[0:15]
	global_load_dwordx4 v[114:117], v[80:81], off offset:768
	global_load_dwordx4 v[118:121], v[78:79], off offset:768
	global_load_dwordx4 v[134:137], v[82:83], off offset:768
	global_load_dwordx4 v[186:189], v[84:85], off offset:768
	global_load_dwordx4 v[190:193], v[86:87], off offset:768
	global_load_dwordx4 v[194:197], v[88:89], off offset:768
	v_mfma_f32_32x32x16_bf16 v[48:63], v[126:129], v[122:125], v[48:63]
	v_mfma_f32_32x32x16_bf16 v[32:47], v[138:141], v[122:125], v[32:47]
	global_load_dwordx4 v[122:125], v[90:91], off offset:768
	global_load_dwordx4 v[198:201], v[92:93], off offset:768
	s_waitcnt lgkmcnt(0)
	s_barrier
	v_mfma_f32_32x32x16_bf16 v[16:31], v[126:129], v[142:145], v[16:31]
	ds_read_b128 v[126:129], v96
	ds_read_b128 v[224:227], v96 offset:4608
	ds_read_b128 v[228:231], v97 offset:18432
	ds_read_b128 v[232:235], v97 offset:23040
	ds_read_b128 v[236:239], v98 offset:32
	ds_read_b128 v[240:243], v98 offset:4640
	ds_read_b128 v[244:247], v99 offset:18464
	ds_read_b128 v[248:251], v99 offset:23072
	v_mfma_f32_32x32x16_bf16 v[0:15], v[138:141], v[142:145], v[0:15]
	s_waitcnt lgkmcnt(5)
	v_mfma_f32_32x32x16_bf16 v[48:63], v[228:231], v[126:129], v[48:63]
	s_waitcnt vmcnt(15)
	ds_write_b128 v95, v[102:105] offset:36864
	s_waitcnt vmcnt(14)
	ds_write_b128 v95, v[106:109] offset:55296
	s_waitcnt vmcnt(13)
	ds_write_b128 v95, v[130:133] offset:41472
	s_waitcnt vmcnt(12)
	ds_write_b128 v95, v[146:149] offset:59904
	s_waitcnt vmcnt(11)
	ds_write_b128 v95, v[212:215] offset:46080
	s_waitcnt vmcnt(10)
	ds_write_b128 v95, v[216:219] offset:64512
	s_waitcnt vmcnt(9)
	ds_write_b128 v95, v[110:113] offset:50688
	s_waitcnt vmcnt(8)
	ds_write_b128 v100, v[220:223] offset:13824
	s_waitcnt lgkmcnt(12)
	v_mfma_f32_32x32x16_bf16 v[32:47], v[232:235], v[126:129], v[32:47]
	ds_read_b128 v[102:105], v99 offset:18496
	ds_read_b128 v[106:109], v98 offset:64
	ds_read_b128 v[110:113], v98 offset:96
	ds_read_b128 v[126:129], v99 offset:18528
	ds_read_b128 v[130:133], v99 offset:23104
	ds_read_b128 v[138:141], v99 offset:23136
	v_mfma_f32_32x32x16_bf16 v[16:31], v[228:231], v[224:227], v[16:31]
	v_mfma_f32_32x32x16_bf16 v[0:15], v[232:235], v[224:227], v[0:15]
	s_waitcnt lgkmcnt(14)
	v_mfma_f32_32x32x16_bf16 v[48:63], v[244:247], v[236:239], v[48:63]
	v_mfma_f32_32x32x16_bf16 v[32:47], v[248:251], v[236:239], v[32:47]
	v_mfma_f32_32x32x16_bf16 v[16:31], v[244:247], v[240:243], v[16:31]
	v_mfma_f32_32x32x16_bf16 v[0:15], v[248:251], v[240:243], v[0:15]
	s_waitcnt lgkmcnt(4)
	v_mfma_f32_32x32x16_bf16 v[48:63], v[102:105], v[106:109], v[48:63]
	s_waitcnt lgkmcnt(1)
	v_mfma_f32_32x32x16_bf16 v[32:47], v[130:133], v[106:109], v[32:47]
	ds_read_b128 v[106:109], v98 offset:4672
	ds_read_b128 v[142:145], v98 offset:4704
	s_waitcnt lgkmcnt(1)
	v_mfma_f32_32x32x16_bf16 v[16:31], v[102:105], v[106:109], v[16:31]
	v_mfma_f32_32x32x16_bf16 v[0:15], v[130:133], v[106:109], v[0:15]
	global_load_dwordx4 v[102:105], v[80:81], off offset:896
	global_load_dwordx4 v[106:109], v[78:79], off offset:896
	global_load_dwordx4 v[130:133], v[82:83], off offset:896
	global_load_dwordx4 v[146:149], v[84:85], off offset:896
	global_load_dwordx4 v[212:215], v[86:87], off offset:896
	global_load_dwordx4 v[216:219], v[88:89], off offset:896
	v_mfma_f32_32x32x16_bf16 v[48:63], v[126:129], v[110:113], v[48:63]
	v_mfma_f32_32x32x16_bf16 v[32:47], v[138:141], v[110:113], v[32:47]
	global_load_dwordx4 v[110:113], v[90:91], off offset:896
	global_load_dwordx4 v[220:223], v[92:93], off offset:896
	s_waitcnt lgkmcnt(0)
	s_barrier
	v_mfma_f32_32x32x16_bf16 v[16:31], v[126:129], v[142:145], v[16:31]
	ds_read_b128 v[126:129], v96 offset:36864
	ds_read_b128 v[224:227], v96 offset:41472
	ds_read_b128 v[228:231], v97 offset:55296
	ds_read_b128 v[232:235], v97 offset:59904
	ds_read_b128 v[236:239], v98 offset:36896
	ds_read_b128 v[240:243], v98 offset:41504
	ds_read_b128 v[244:247], v99 offset:55328
	ds_read_b128 v[248:251], v99 offset:59936
	v_mfma_f32_32x32x16_bf16 v[0:15], v[138:141], v[142:145], v[0:15]
	s_waitcnt lgkmcnt(5)
	v_mfma_f32_32x32x16_bf16 v[48:63], v[228:231], v[126:129], v[48:63]
	s_waitcnt vmcnt(15)
	ds_write_b128 v95, v[114:117]
	s_waitcnt vmcnt(14)
	ds_write_b128 v95, v[118:121] offset:18432
	s_waitcnt vmcnt(13)
	ds_write_b128 v95, v[134:137] offset:4608
	s_waitcnt vmcnt(12)
	ds_write_b128 v95, v[186:189] offset:23040
	s_waitcnt vmcnt(11)
	ds_write_b128 v95, v[190:193] offset:9216
	s_waitcnt vmcnt(10)
	ds_write_b128 v95, v[194:197] offset:27648
	s_waitcnt vmcnt(9)
	ds_write_b128 v95, v[122:125] offset:13824
	s_waitcnt vmcnt(8)
	ds_write_b128 v95, v[198:201] offset:32256
	s_waitcnt lgkmcnt(12)
	v_mfma_f32_32x32x16_bf16 v[32:47], v[232:235], v[126:129], v[32:47]
	ds_read_b128 v[114:117], v99 offset:55360
	ds_read_b128 v[118:121], v98 offset:36928
	ds_read_b128 v[122:125], v98 offset:36960
	ds_read_b128 v[126:129], v99 offset:55392
	ds_read_b128 v[134:137], v99 offset:59968
	ds_read_b128 v[138:141], v99 offset:60000
	v_mfma_f32_32x32x16_bf16 v[16:31], v[228:231], v[224:227], v[16:31]
	v_mfma_f32_32x32x16_bf16 v[0:15], v[232:235], v[224:227], v[0:15]
	s_waitcnt lgkmcnt(14)
	v_mfma_f32_32x32x16_bf16 v[48:63], v[244:247], v[236:239], v[48:63]
	v_mfma_f32_32x32x16_bf16 v[32:47], v[248:251], v[236:239], v[32:47]
	v_mfma_f32_32x32x16_bf16 v[16:31], v[244:247], v[240:243], v[16:31]
	v_mfma_f32_32x32x16_bf16 v[0:15], v[248:251], v[240:243], v[0:15]
	s_waitcnt lgkmcnt(4)
	v_mfma_f32_32x32x16_bf16 v[48:63], v[114:117], v[118:121], v[48:63]
	s_waitcnt lgkmcnt(1)
	v_mfma_f32_32x32x16_bf16 v[32:47], v[134:137], v[118:121], v[32:47]
	ds_read_b128 v[118:121], v98 offset:41536
	ds_read_b128 v[142:145], v98 offset:41568
	s_waitcnt lgkmcnt(1)
	v_mfma_f32_32x32x16_bf16 v[16:31], v[114:117], v[118:121], v[16:31]
	v_mfma_f32_32x32x16_bf16 v[0:15], v[134:137], v[118:121], v[0:15]
	global_load_dwordx4 v[114:117], v[80:81], off offset:1024
	global_load_dwordx4 v[118:121], v[78:79], off offset:1024
	global_load_dwordx4 v[134:137], v[82:83], off offset:1024
	global_load_dwordx4 v[186:189], v[84:85], off offset:1024
	global_load_dwordx4 v[190:193], v[86:87], off offset:1024
	global_load_dwordx4 v[194:197], v[88:89], off offset:1024
	v_mfma_f32_32x32x16_bf16 v[48:63], v[126:129], v[122:125], v[48:63]
	v_mfma_f32_32x32x16_bf16 v[32:47], v[138:141], v[122:125], v[32:47]
	global_load_dwordx4 v[122:125], v[90:91], off offset:1024
	global_load_dwordx4 v[198:201], v[92:93], off offset:1024
	s_waitcnt lgkmcnt(0)
	s_barrier
	v_mfma_f32_32x32x16_bf16 v[16:31], v[126:129], v[142:145], v[16:31]
	ds_read_b128 v[126:129], v96
	ds_read_b128 v[224:227], v96 offset:4608
	ds_read_b128 v[228:231], v97 offset:18432
	ds_read_b128 v[232:235], v97 offset:23040
	ds_read_b128 v[236:239], v98 offset:32
	ds_read_b128 v[240:243], v98 offset:4640
	ds_read_b128 v[244:247], v99 offset:18464
	ds_read_b128 v[248:251], v99 offset:23072
	v_mfma_f32_32x32x16_bf16 v[0:15], v[138:141], v[142:145], v[0:15]
	s_waitcnt lgkmcnt(5)
	v_mfma_f32_32x32x16_bf16 v[48:63], v[228:231], v[126:129], v[48:63]
	s_waitcnt vmcnt(15)
	ds_write_b128 v95, v[102:105] offset:36864
	s_waitcnt vmcnt(14)
	ds_write_b128 v95, v[106:109] offset:55296
	s_waitcnt vmcnt(13)
	ds_write_b128 v95, v[130:133] offset:41472
	s_waitcnt vmcnt(12)
	ds_write_b128 v95, v[146:149] offset:59904
	s_waitcnt vmcnt(11)
	ds_write_b128 v95, v[212:215] offset:46080
	s_waitcnt vmcnt(10)
	ds_write_b128 v95, v[216:219] offset:64512
	s_waitcnt vmcnt(9)
	ds_write_b128 v95, v[110:113] offset:50688
	s_waitcnt vmcnt(8)
	ds_write_b128 v100, v[220:223] offset:13824
	s_waitcnt lgkmcnt(12)
	v_mfma_f32_32x32x16_bf16 v[32:47], v[232:235], v[126:129], v[32:47]
	ds_read_b128 v[102:105], v99 offset:18496
	ds_read_b128 v[106:109], v98 offset:64
	ds_read_b128 v[110:113], v98 offset:96
	ds_read_b128 v[126:129], v99 offset:18528
	ds_read_b128 v[130:133], v99 offset:23104
	ds_read_b128 v[138:141], v99 offset:23136
	v_mfma_f32_32x32x16_bf16 v[16:31], v[228:231], v[224:227], v[16:31]
	v_mfma_f32_32x32x16_bf16 v[0:15], v[232:235], v[224:227], v[0:15]
	s_waitcnt lgkmcnt(14)
	v_mfma_f32_32x32x16_bf16 v[48:63], v[244:247], v[236:239], v[48:63]
	v_mfma_f32_32x32x16_bf16 v[32:47], v[248:251], v[236:239], v[32:47]
	v_mfma_f32_32x32x16_bf16 v[16:31], v[244:247], v[240:243], v[16:31]
	v_mfma_f32_32x32x16_bf16 v[0:15], v[248:251], v[240:243], v[0:15]
	s_waitcnt lgkmcnt(4)
	v_mfma_f32_32x32x16_bf16 v[48:63], v[102:105], v[106:109], v[48:63]
	s_waitcnt lgkmcnt(1)
	v_mfma_f32_32x32x16_bf16 v[32:47], v[130:133], v[106:109], v[32:47]
	ds_read_b128 v[106:109], v98 offset:4672
	ds_read_b128 v[142:145], v98 offset:4704
	s_waitcnt lgkmcnt(1)
	v_mfma_f32_32x32x16_bf16 v[16:31], v[102:105], v[106:109], v[16:31]
	v_mfma_f32_32x32x16_bf16 v[0:15], v[130:133], v[106:109], v[0:15]
	global_load_dwordx4 v[102:105], v[80:81], off offset:1152
	global_load_dwordx4 v[106:109], v[78:79], off offset:1152
	global_load_dwordx4 v[130:133], v[82:83], off offset:1152
	global_load_dwordx4 v[146:149], v[84:85], off offset:1152
	global_load_dwordx4 v[212:215], v[86:87], off offset:1152
	global_load_dwordx4 v[216:219], v[88:89], off offset:1152
	v_mfma_f32_32x32x16_bf16 v[48:63], v[126:129], v[110:113], v[48:63]
	v_mfma_f32_32x32x16_bf16 v[32:47], v[138:141], v[110:113], v[32:47]
	global_load_dwordx4 v[110:113], v[90:91], off offset:1152
	global_load_dwordx4 v[220:223], v[92:93], off offset:1152
	s_waitcnt lgkmcnt(0)
	s_barrier
	v_mfma_f32_32x32x16_bf16 v[16:31], v[126:129], v[142:145], v[16:31]
	ds_read_b128 v[126:129], v96 offset:36864
	ds_read_b128 v[224:227], v96 offset:41472
	ds_read_b128 v[228:231], v97 offset:55296
	ds_read_b128 v[232:235], v97 offset:59904
	ds_read_b128 v[236:239], v98 offset:36896
	ds_read_b128 v[240:243], v98 offset:41504
	ds_read_b128 v[244:247], v99 offset:55328
	ds_read_b128 v[248:251], v99 offset:59936
	v_mfma_f32_32x32x16_bf16 v[0:15], v[138:141], v[142:145], v[0:15]
	s_waitcnt lgkmcnt(5)
	v_mfma_f32_32x32x16_bf16 v[48:63], v[228:231], v[126:129], v[48:63]
	s_waitcnt vmcnt(15)
	ds_write_b128 v95, v[114:117]
	s_waitcnt vmcnt(14)
	ds_write_b128 v95, v[118:121] offset:18432
	s_waitcnt vmcnt(13)
	ds_write_b128 v95, v[134:137] offset:4608
	s_waitcnt vmcnt(12)
	ds_write_b128 v95, v[186:189] offset:23040
	s_waitcnt vmcnt(11)
	ds_write_b128 v95, v[190:193] offset:9216
	s_waitcnt vmcnt(10)
	ds_write_b128 v95, v[194:197] offset:27648
	s_waitcnt vmcnt(9)
	ds_write_b128 v95, v[122:125] offset:13824
	s_waitcnt vmcnt(8)
	ds_write_b128 v95, v[198:201] offset:32256
	s_waitcnt lgkmcnt(12)
	v_mfma_f32_32x32x16_bf16 v[32:47], v[232:235], v[126:129], v[32:47]
	ds_read_b128 v[114:117], v99 offset:55360
	ds_read_b128 v[118:121], v98 offset:36928
	ds_read_b128 v[122:125], v98 offset:36960
	ds_read_b128 v[126:129], v99 offset:55392
	ds_read_b128 v[134:137], v99 offset:59968
	ds_read_b128 v[138:141], v99 offset:60000
	v_mfma_f32_32x32x16_bf16 v[16:31], v[228:231], v[224:227], v[16:31]
	v_mfma_f32_32x32x16_bf16 v[0:15], v[232:235], v[224:227], v[0:15]
	s_waitcnt lgkmcnt(14)
	v_mfma_f32_32x32x16_bf16 v[48:63], v[244:247], v[236:239], v[48:63]
	v_mfma_f32_32x32x16_bf16 v[32:47], v[248:251], v[236:239], v[32:47]
	v_mfma_f32_32x32x16_bf16 v[16:31], v[244:247], v[240:243], v[16:31]
	v_mfma_f32_32x32x16_bf16 v[0:15], v[248:251], v[240:243], v[0:15]
	s_waitcnt lgkmcnt(4)
	v_mfma_f32_32x32x16_bf16 v[48:63], v[114:117], v[118:121], v[48:63]
	s_waitcnt lgkmcnt(1)
	v_mfma_f32_32x32x16_bf16 v[32:47], v[134:137], v[118:121], v[32:47]
	ds_read_b128 v[118:121], v98 offset:41536
	ds_read_b128 v[142:145], v98 offset:41568
	s_waitcnt lgkmcnt(1)
	v_mfma_f32_32x32x16_bf16 v[16:31], v[114:117], v[118:121], v[16:31]
	v_mfma_f32_32x32x16_bf16 v[0:15], v[134:137], v[118:121], v[0:15]
	global_load_dwordx4 v[114:117], v[80:81], off offset:1280
	global_load_dwordx4 v[118:121], v[78:79], off offset:1280
	global_load_dwordx4 v[134:137], v[82:83], off offset:1280
	global_load_dwordx4 v[186:189], v[84:85], off offset:1280
	global_load_dwordx4 v[190:193], v[86:87], off offset:1280
	global_load_dwordx4 v[194:197], v[88:89], off offset:1280
	v_mfma_f32_32x32x16_bf16 v[48:63], v[126:129], v[122:125], v[48:63]
	v_mfma_f32_32x32x16_bf16 v[32:47], v[138:141], v[122:125], v[32:47]
	global_load_dwordx4 v[122:125], v[90:91], off offset:1280
	global_load_dwordx4 v[198:201], v[92:93], off offset:1280
	s_waitcnt lgkmcnt(0)
	s_barrier
	v_mfma_f32_32x32x16_bf16 v[16:31], v[126:129], v[142:145], v[16:31]
	ds_read_b128 v[126:129], v96
	ds_read_b128 v[224:227], v96 offset:4608
	ds_read_b128 v[228:231], v97 offset:18432
	ds_read_b128 v[232:235], v97 offset:23040
	ds_read_b128 v[236:239], v98 offset:32
	ds_read_b128 v[240:243], v98 offset:4640
	ds_read_b128 v[244:247], v99 offset:18464
	ds_read_b128 v[248:251], v99 offset:23072
	v_mfma_f32_32x32x16_bf16 v[0:15], v[138:141], v[142:145], v[0:15]
	s_waitcnt lgkmcnt(5)
	v_mfma_f32_32x32x16_bf16 v[48:63], v[228:231], v[126:129], v[48:63]
	s_waitcnt vmcnt(15)
	ds_write_b128 v95, v[102:105] offset:36864
	s_waitcnt vmcnt(14)
	ds_write_b128 v95, v[106:109] offset:55296
	s_waitcnt vmcnt(13)
	ds_write_b128 v95, v[130:133] offset:41472
	s_waitcnt vmcnt(12)
	ds_write_b128 v95, v[146:149] offset:59904
	s_waitcnt vmcnt(11)
	ds_write_b128 v95, v[212:215] offset:46080
	s_waitcnt vmcnt(10)
	ds_write_b128 v95, v[216:219] offset:64512
	s_waitcnt vmcnt(9)
	ds_write_b128 v95, v[110:113] offset:50688
	s_waitcnt vmcnt(8)
	ds_write_b128 v100, v[220:223] offset:13824
	s_waitcnt lgkmcnt(12)
	v_mfma_f32_32x32x16_bf16 v[32:47], v[232:235], v[126:129], v[32:47]
	ds_read_b128 v[102:105], v99 offset:18496
	ds_read_b128 v[106:109], v98 offset:64
	ds_read_b128 v[110:113], v98 offset:96
	ds_read_b128 v[126:129], v99 offset:18528
	ds_read_b128 v[130:133], v99 offset:23104
	ds_read_b128 v[138:141], v99 offset:23136
	v_mfma_f32_32x32x16_bf16 v[16:31], v[228:231], v[224:227], v[16:31]
	v_mfma_f32_32x32x16_bf16 v[0:15], v[232:235], v[224:227], v[0:15]
	s_waitcnt lgkmcnt(14)
	v_mfma_f32_32x32x16_bf16 v[48:63], v[244:247], v[236:239], v[48:63]
	v_mfma_f32_32x32x16_bf16 v[32:47], v[248:251], v[236:239], v[32:47]
	v_mfma_f32_32x32x16_bf16 v[16:31], v[244:247], v[240:243], v[16:31]
	v_mfma_f32_32x32x16_bf16 v[0:15], v[248:251], v[240:243], v[0:15]
	s_waitcnt lgkmcnt(4)
	v_mfma_f32_32x32x16_bf16 v[48:63], v[102:105], v[106:109], v[48:63]
	s_waitcnt lgkmcnt(1)
	v_mfma_f32_32x32x16_bf16 v[32:47], v[130:133], v[106:109], v[32:47]
	ds_read_b128 v[106:109], v98 offset:4672
	ds_read_b128 v[142:145], v98 offset:4704
	s_waitcnt lgkmcnt(1)
	v_mfma_f32_32x32x16_bf16 v[16:31], v[102:105], v[106:109], v[16:31]
	v_mfma_f32_32x32x16_bf16 v[0:15], v[130:133], v[106:109], v[0:15]
	global_load_dwordx4 v[102:105], v[80:81], off offset:1408
	global_load_dwordx4 v[106:109], v[78:79], off offset:1408
	global_load_dwordx4 v[130:133], v[82:83], off offset:1408
	global_load_dwordx4 v[146:149], v[84:85], off offset:1408
	global_load_dwordx4 v[212:215], v[86:87], off offset:1408
	global_load_dwordx4 v[216:219], v[88:89], off offset:1408
	v_mfma_f32_32x32x16_bf16 v[48:63], v[126:129], v[110:113], v[48:63]
	v_mfma_f32_32x32x16_bf16 v[32:47], v[138:141], v[110:113], v[32:47]
	global_load_dwordx4 v[110:113], v[90:91], off offset:1408
	global_load_dwordx4 v[220:223], v[92:93], off offset:1408
	s_waitcnt lgkmcnt(0)
	s_barrier
	v_mfma_f32_32x32x16_bf16 v[16:31], v[126:129], v[142:145], v[16:31]
	ds_read_b128 v[126:129], v96 offset:36864
	ds_read_b128 v[224:227], v96 offset:41472
	ds_read_b128 v[228:231], v97 offset:55296
	ds_read_b128 v[232:235], v97 offset:59904
	ds_read_b128 v[236:239], v98 offset:36896
	ds_read_b128 v[240:243], v98 offset:41504
	ds_read_b128 v[244:247], v99 offset:55328
	ds_read_b128 v[248:251], v99 offset:59936
	v_mfma_f32_32x32x16_bf16 v[0:15], v[138:141], v[142:145], v[0:15]
	s_waitcnt lgkmcnt(5)
	v_mfma_f32_32x32x16_bf16 v[48:63], v[228:231], v[126:129], v[48:63]
	s_waitcnt vmcnt(15)
	ds_write_b128 v95, v[114:117]
	s_waitcnt vmcnt(14)
	ds_write_b128 v95, v[118:121] offset:18432
	s_waitcnt vmcnt(13)
	ds_write_b128 v95, v[134:137] offset:4608
	s_waitcnt vmcnt(12)
	ds_write_b128 v95, v[186:189] offset:23040
	s_waitcnt vmcnt(11)
	ds_write_b128 v95, v[190:193] offset:9216
	s_waitcnt vmcnt(10)
	ds_write_b128 v95, v[194:197] offset:27648
	s_waitcnt vmcnt(9)
	ds_write_b128 v95, v[122:125] offset:13824
	s_waitcnt vmcnt(8)
	ds_write_b128 v95, v[198:201] offset:32256
	s_waitcnt lgkmcnt(12)
	v_mfma_f32_32x32x16_bf16 v[32:47], v[232:235], v[126:129], v[32:47]
	ds_read_b128 v[114:117], v99 offset:55360
	ds_read_b128 v[118:121], v98 offset:36928
	ds_read_b128 v[122:125], v98 offset:36960
	ds_read_b128 v[126:129], v99 offset:55392
	ds_read_b128 v[134:137], v99 offset:59968
	ds_read_b128 v[138:141], v99 offset:60000
	v_mfma_f32_32x32x16_bf16 v[16:31], v[228:231], v[224:227], v[16:31]
	v_mfma_f32_32x32x16_bf16 v[0:15], v[232:235], v[224:227], v[0:15]
	s_waitcnt lgkmcnt(14)
	v_mfma_f32_32x32x16_bf16 v[48:63], v[244:247], v[236:239], v[48:63]
	v_mfma_f32_32x32x16_bf16 v[32:47], v[248:251], v[236:239], v[32:47]
	v_mfma_f32_32x32x16_bf16 v[16:31], v[244:247], v[240:243], v[16:31]
	v_mfma_f32_32x32x16_bf16 v[0:15], v[248:251], v[240:243], v[0:15]
	s_waitcnt lgkmcnt(4)
	v_mfma_f32_32x32x16_bf16 v[48:63], v[114:117], v[118:121], v[48:63]
	s_waitcnt lgkmcnt(1)
	v_mfma_f32_32x32x16_bf16 v[32:47], v[134:137], v[118:121], v[32:47]
	ds_read_b128 v[118:121], v98 offset:41536
	ds_read_b128 v[142:145], v98 offset:41568
	s_waitcnt lgkmcnt(1)
	v_mfma_f32_32x32x16_bf16 v[16:31], v[114:117], v[118:121], v[16:31]
	v_mfma_f32_32x32x16_bf16 v[0:15], v[134:137], v[118:121], v[0:15]
	global_load_dwordx4 v[114:117], v[80:81], off offset:1536
	global_load_dwordx4 v[118:121], v[78:79], off offset:1536
	global_load_dwordx4 v[134:137], v[82:83], off offset:1536
	global_load_dwordx4 v[186:189], v[84:85], off offset:1536
	global_load_dwordx4 v[190:193], v[86:87], off offset:1536
	global_load_dwordx4 v[194:197], v[88:89], off offset:1536
	v_mfma_f32_32x32x16_bf16 v[48:63], v[126:129], v[122:125], v[48:63]
	v_mfma_f32_32x32x16_bf16 v[32:47], v[138:141], v[122:125], v[32:47]
	global_load_dwordx4 v[122:125], v[90:91], off offset:1536
	global_load_dwordx4 v[198:201], v[92:93], off offset:1536
	s_waitcnt lgkmcnt(0)
	s_barrier
	v_mfma_f32_32x32x16_bf16 v[16:31], v[126:129], v[142:145], v[16:31]
	ds_read_b128 v[126:129], v96
	ds_read_b128 v[224:227], v96 offset:4608
	ds_read_b128 v[228:231], v97 offset:18432
	ds_read_b128 v[232:235], v97 offset:23040
	ds_read_b128 v[236:239], v98 offset:32
	ds_read_b128 v[240:243], v98 offset:4640
	ds_read_b128 v[244:247], v99 offset:18464
	ds_read_b128 v[248:251], v99 offset:23072
	v_mfma_f32_32x32x16_bf16 v[0:15], v[138:141], v[142:145], v[0:15]
	s_waitcnt lgkmcnt(5)
	v_mfma_f32_32x32x16_bf16 v[48:63], v[228:231], v[126:129], v[48:63]
	s_waitcnt vmcnt(15)
	ds_write_b128 v95, v[102:105] offset:36864
	s_waitcnt vmcnt(14)
	ds_write_b128 v95, v[106:109] offset:55296
	s_waitcnt vmcnt(13)
	ds_write_b128 v95, v[130:133] offset:41472
	s_waitcnt vmcnt(12)
	ds_write_b128 v95, v[146:149] offset:59904
	s_waitcnt vmcnt(11)
	ds_write_b128 v95, v[212:215] offset:46080
	s_waitcnt vmcnt(10)
	ds_write_b128 v95, v[216:219] offset:64512
	s_waitcnt vmcnt(9)
	ds_write_b128 v95, v[110:113] offset:50688
	s_waitcnt vmcnt(8)
	ds_write_b128 v100, v[220:223] offset:13824
	s_waitcnt lgkmcnt(12)
	v_mfma_f32_32x32x16_bf16 v[32:47], v[232:235], v[126:129], v[32:47]
	ds_read_b128 v[102:105], v99 offset:18496
	ds_read_b128 v[106:109], v98 offset:64
	ds_read_b128 v[110:113], v98 offset:96
	ds_read_b128 v[126:129], v99 offset:18528
	ds_read_b128 v[130:133], v99 offset:23104
	ds_read_b128 v[138:141], v99 offset:23136
	v_mfma_f32_32x32x16_bf16 v[16:31], v[228:231], v[224:227], v[16:31]
	v_mfma_f32_32x32x16_bf16 v[0:15], v[232:235], v[224:227], v[0:15]
	s_waitcnt lgkmcnt(14)
	v_mfma_f32_32x32x16_bf16 v[48:63], v[244:247], v[236:239], v[48:63]
	v_mfma_f32_32x32x16_bf16 v[32:47], v[248:251], v[236:239], v[32:47]
	v_mfma_f32_32x32x16_bf16 v[16:31], v[244:247], v[240:243], v[16:31]
	v_mfma_f32_32x32x16_bf16 v[0:15], v[248:251], v[240:243], v[0:15]
	s_waitcnt lgkmcnt(4)
	v_mfma_f32_32x32x16_bf16 v[48:63], v[102:105], v[106:109], v[48:63]
	s_waitcnt lgkmcnt(1)
	v_mfma_f32_32x32x16_bf16 v[32:47], v[130:133], v[106:109], v[32:47]
	ds_read_b128 v[106:109], v98 offset:4672
	ds_read_b128 v[142:145], v98 offset:4704
	s_waitcnt lgkmcnt(1)
	v_mfma_f32_32x32x16_bf16 v[16:31], v[102:105], v[106:109], v[16:31]
	v_mfma_f32_32x32x16_bf16 v[0:15], v[130:133], v[106:109], v[0:15]
	global_load_dwordx4 v[102:105], v[80:81], off offset:1664
	global_load_dwordx4 v[106:109], v[78:79], off offset:1664
	global_load_dwordx4 v[130:133], v[82:83], off offset:1664
	global_load_dwordx4 v[146:149], v[84:85], off offset:1664
	global_load_dwordx4 v[212:215], v[86:87], off offset:1664
	global_load_dwordx4 v[216:219], v[88:89], off offset:1664
	v_mfma_f32_32x32x16_bf16 v[48:63], v[126:129], v[110:113], v[48:63]
	v_mfma_f32_32x32x16_bf16 v[32:47], v[138:141], v[110:113], v[32:47]
	global_load_dwordx4 v[110:113], v[90:91], off offset:1664
	global_load_dwordx4 v[220:223], v[92:93], off offset:1664
	s_waitcnt lgkmcnt(0)
	s_barrier
	v_mfma_f32_32x32x16_bf16 v[16:31], v[126:129], v[142:145], v[16:31]
	ds_read_b128 v[126:129], v96 offset:36864
	ds_read_b128 v[224:227], v96 offset:41472
	ds_read_b128 v[228:231], v97 offset:55296
	ds_read_b128 v[232:235], v97 offset:59904
	ds_read_b128 v[236:239], v98 offset:36896
	ds_read_b128 v[240:243], v98 offset:41504
	ds_read_b128 v[244:247], v99 offset:55328
	ds_read_b128 v[248:251], v99 offset:59936
	v_mfma_f32_32x32x16_bf16 v[0:15], v[138:141], v[142:145], v[0:15]
	s_waitcnt lgkmcnt(5)
	v_mfma_f32_32x32x16_bf16 v[48:63], v[228:231], v[126:129], v[48:63]
	s_waitcnt vmcnt(15)
	ds_write_b128 v95, v[114:117]
	s_waitcnt vmcnt(14)
	ds_write_b128 v95, v[118:121] offset:18432
	s_waitcnt vmcnt(13)
	ds_write_b128 v95, v[134:137] offset:4608
	s_waitcnt vmcnt(12)
	ds_write_b128 v95, v[186:189] offset:23040
	s_waitcnt vmcnt(11)
	ds_write_b128 v95, v[190:193] offset:9216
	s_waitcnt vmcnt(10)
	ds_write_b128 v95, v[194:197] offset:27648
	s_waitcnt vmcnt(9)
	ds_write_b128 v95, v[122:125] offset:13824
	s_waitcnt vmcnt(8)
	ds_write_b128 v95, v[198:201] offset:32256
	s_waitcnt lgkmcnt(12)
	v_mfma_f32_32x32x16_bf16 v[32:47], v[232:235], v[126:129], v[32:47]
	ds_read_b128 v[114:117], v99 offset:55360
	ds_read_b128 v[118:121], v98 offset:36928
	ds_read_b128 v[122:125], v98 offset:36960
	ds_read_b128 v[126:129], v99 offset:55392
	ds_read_b128 v[134:137], v99 offset:59968
	ds_read_b128 v[138:141], v99 offset:60000
	v_mfma_f32_32x32x16_bf16 v[16:31], v[228:231], v[224:227], v[16:31]
	v_mfma_f32_32x32x16_bf16 v[0:15], v[232:235], v[224:227], v[0:15]
	s_waitcnt lgkmcnt(14)
	v_mfma_f32_32x32x16_bf16 v[48:63], v[244:247], v[236:239], v[48:63]
	v_mfma_f32_32x32x16_bf16 v[32:47], v[248:251], v[236:239], v[32:47]
	v_mfma_f32_32x32x16_bf16 v[16:31], v[244:247], v[240:243], v[16:31]
	v_mfma_f32_32x32x16_bf16 v[0:15], v[248:251], v[240:243], v[0:15]
	s_waitcnt lgkmcnt(4)
	v_mfma_f32_32x32x16_bf16 v[48:63], v[114:117], v[118:121], v[48:63]
	s_waitcnt lgkmcnt(1)
	v_mfma_f32_32x32x16_bf16 v[32:47], v[134:137], v[118:121], v[32:47]
	ds_read_b128 v[118:121], v98 offset:41536
	ds_read_b128 v[142:145], v98 offset:41568
	s_waitcnt lgkmcnt(1)
	v_mfma_f32_32x32x16_bf16 v[16:31], v[114:117], v[118:121], v[16:31]
	v_mfma_f32_32x32x16_bf16 v[0:15], v[134:137], v[118:121], v[0:15]
	global_load_dwordx4 v[114:117], v[80:81], off offset:1792
	global_load_dwordx4 v[118:121], v[78:79], off offset:1792
	global_load_dwordx4 v[134:137], v[82:83], off offset:1792
	global_load_dwordx4 v[186:189], v[84:85], off offset:1792
	global_load_dwordx4 v[190:193], v[86:87], off offset:1792
	global_load_dwordx4 v[194:197], v[88:89], off offset:1792
	v_mfma_f32_32x32x16_bf16 v[48:63], v[126:129], v[122:125], v[48:63]
	v_mfma_f32_32x32x16_bf16 v[32:47], v[138:141], v[122:125], v[32:47]
	global_load_dwordx4 v[122:125], v[90:91], off offset:1792
	global_load_dwordx4 v[198:201], v[92:93], off offset:1792
	s_waitcnt lgkmcnt(0)
	s_barrier
	v_mfma_f32_32x32x16_bf16 v[16:31], v[126:129], v[142:145], v[16:31]
	ds_read_b128 v[126:129], v96
	ds_read_b128 v[224:227], v96 offset:4608
	ds_read_b128 v[228:231], v97 offset:18432
	ds_read_b128 v[232:235], v97 offset:23040
	ds_read_b128 v[236:239], v98 offset:32
	ds_read_b128 v[240:243], v98 offset:4640
	ds_read_b128 v[244:247], v99 offset:18464
	ds_read_b128 v[248:251], v99 offset:23072
	v_mfma_f32_32x32x16_bf16 v[0:15], v[138:141], v[142:145], v[0:15]
	s_waitcnt lgkmcnt(5)
	v_mfma_f32_32x32x16_bf16 v[48:63], v[228:231], v[126:129], v[48:63]
	s_waitcnt vmcnt(15)
	ds_write_b128 v95, v[102:105] offset:36864
	s_waitcnt vmcnt(14)
	ds_write_b128 v95, v[106:109] offset:55296
	s_waitcnt vmcnt(13)
	ds_write_b128 v95, v[130:133] offset:41472
	s_waitcnt vmcnt(12)
	ds_write_b128 v95, v[146:149] offset:59904
	s_waitcnt vmcnt(11)
	ds_write_b128 v95, v[212:215] offset:46080
	s_waitcnt vmcnt(10)
	ds_write_b128 v95, v[216:219] offset:64512
	s_waitcnt vmcnt(9)
	ds_write_b128 v95, v[110:113] offset:50688
	s_waitcnt vmcnt(8)
	ds_write_b128 v100, v[220:223] offset:13824
	s_waitcnt lgkmcnt(12)
	v_mfma_f32_32x32x16_bf16 v[32:47], v[232:235], v[126:129], v[32:47]
	ds_read_b128 v[102:105], v99 offset:18496
	ds_read_b128 v[106:109], v98 offset:64
	ds_read_b128 v[110:113], v98 offset:96
	ds_read_b128 v[126:129], v99 offset:18528
	ds_read_b128 v[130:133], v99 offset:23104
	ds_read_b128 v[138:141], v99 offset:23136
	v_mfma_f32_32x32x16_bf16 v[16:31], v[228:231], v[224:227], v[16:31]
	v_mfma_f32_32x32x16_bf16 v[0:15], v[232:235], v[224:227], v[0:15]
	s_waitcnt lgkmcnt(14)
	v_mfma_f32_32x32x16_bf16 v[48:63], v[244:247], v[236:239], v[48:63]
	v_mfma_f32_32x32x16_bf16 v[32:47], v[248:251], v[236:239], v[32:47]
	v_mfma_f32_32x32x16_bf16 v[16:31], v[244:247], v[240:243], v[16:31]
	v_mfma_f32_32x32x16_bf16 v[0:15], v[248:251], v[240:243], v[0:15]
	s_waitcnt lgkmcnt(4)
	v_mfma_f32_32x32x16_bf16 v[48:63], v[102:105], v[106:109], v[48:63]
	s_waitcnt lgkmcnt(1)
	v_mfma_f32_32x32x16_bf16 v[32:47], v[130:133], v[106:109], v[32:47]
	ds_read_b128 v[106:109], v98 offset:4672
	ds_read_b128 v[142:145], v98 offset:4704
	s_waitcnt lgkmcnt(1)
	v_mfma_f32_32x32x16_bf16 v[16:31], v[102:105], v[106:109], v[16:31]
	v_mfma_f32_32x32x16_bf16 v[0:15], v[130:133], v[106:109], v[0:15]
	global_load_dwordx4 v[102:105], v[80:81], off offset:1920
	s_nop 0
	global_load_dwordx4 v[78:81], v[78:79], off offset:1920
	s_nop 0
	global_load_dwordx4 v[106:109], v[82:83], off offset:1920
	s_nop 0
	global_load_dwordx4 v[82:85], v[84:85], off offset:1920
	s_nop 0
	global_load_dwordx4 v[130:133], v[86:87], off offset:1920
	s_nop 0
	global_load_dwordx4 v[86:89], v[88:89], off offset:1920
	v_mfma_f32_32x32x16_bf16 v[48:63], v[126:129], v[110:113], v[48:63]
	v_mfma_f32_32x32x16_bf16 v[32:47], v[138:141], v[110:113], v[32:47]
	global_load_dwordx4 v[110:113], v[90:91], off offset:1920
	s_nop 0
	global_load_dwordx4 v[90:93], v[92:93], off offset:1920
	s_waitcnt lgkmcnt(0)
	s_barrier
	v_mfma_f32_32x32x16_bf16 v[16:31], v[126:129], v[142:145], v[16:31]
	ds_read_b128 v[126:129], v96 offset:36864
	ds_read_b128 v[146:149], v96 offset:41472
	ds_read_b128 v[212:215], v97 offset:55296
	ds_read_b128 v[216:219], v97 offset:59904
	ds_read_b128 v[220:223], v98 offset:36896
	ds_read_b128 v[224:227], v98 offset:41504
	ds_read_b128 v[228:231], v99 offset:55328
	ds_read_b128 v[232:235], v99 offset:59936
	v_mfma_f32_32x32x16_bf16 v[0:15], v[138:141], v[142:145], v[0:15]
	s_waitcnt lgkmcnt(5)
	v_mfma_f32_32x32x16_bf16 v[48:63], v[212:215], v[126:129], v[48:63]
	s_waitcnt vmcnt(15)
	ds_write_b128 v95, v[114:117]
	s_waitcnt vmcnt(14)
	ds_write_b128 v95, v[118:121] offset:18432
	s_waitcnt vmcnt(13)
	ds_write_b128 v95, v[134:137] offset:4608
	s_waitcnt vmcnt(12)
	ds_write_b128 v95, v[186:189] offset:23040
	s_waitcnt vmcnt(11)
	ds_write_b128 v95, v[190:193] offset:9216
	s_waitcnt vmcnt(10)
	ds_write_b128 v95, v[194:197] offset:27648
	s_waitcnt vmcnt(9)
	ds_write_b128 v95, v[122:125] offset:13824
	s_waitcnt vmcnt(8)
	ds_write_b128 v95, v[198:201] offset:32256
	s_waitcnt lgkmcnt(12)
	v_mfma_f32_32x32x16_bf16 v[32:47], v[216:219], v[126:129], v[32:47]
	ds_read_b128 v[114:117], v99 offset:55360
	ds_read_b128 v[118:121], v98 offset:36928
	ds_read_b128 v[122:125], v98 offset:36960
	ds_read_b128 v[126:129], v99 offset:55392
	ds_read_b128 v[134:137], v99 offset:59968
	ds_read_b128 v[138:141], v99 offset:60000
	v_mfma_f32_32x32x16_bf16 v[16:31], v[212:215], v[146:149], v[16:31]
	v_mfma_f32_32x32x16_bf16 v[0:15], v[216:219], v[146:149], v[0:15]
	s_waitcnt lgkmcnt(14)
	v_mfma_f32_32x32x16_bf16 v[48:63], v[228:231], v[220:223], v[48:63]
	v_mfma_f32_32x32x16_bf16 v[32:47], v[232:235], v[220:223], v[32:47]
	v_mfma_f32_32x32x16_bf16 v[16:31], v[228:231], v[224:227], v[16:31]
	v_mfma_f32_32x32x16_bf16 v[0:15], v[232:235], v[224:227], v[0:15]
	s_waitcnt lgkmcnt(4)
	v_mfma_f32_32x32x16_bf16 v[48:63], v[114:117], v[118:121], v[48:63]
	s_waitcnt lgkmcnt(1)
	v_mfma_f32_32x32x16_bf16 v[32:47], v[134:137], v[118:121], v[32:47]
	ds_read_b128 v[118:121], v98 offset:41536
	ds_read_b128 v[142:145], v98 offset:41568
	s_waitcnt lgkmcnt(0)
	s_barrier
	v_mfma_f32_32x32x16_bf16 v[16:31], v[114:117], v[118:121], v[16:31]
	v_mfma_f32_32x32x16_bf16 v[0:15], v[134:137], v[118:121], v[0:15]
	v_mfma_f32_32x32x16_bf16 v[48:63], v[126:129], v[122:125], v[48:63]
	v_mfma_f32_32x32x16_bf16 v[32:47], v[138:141], v[122:125], v[32:47]
	v_mfma_f32_32x32x16_bf16 v[16:31], v[126:129], v[142:145], v[16:31]
	ds_read_b128 v[114:117], v96
	ds_read_b128 v[118:121], v96 offset:4608
	ds_read_b128 v[122:125], v97 offset:18432
	ds_read_b128 v[126:129], v97 offset:23040
	ds_read_b128 v[134:137], v98 offset:32
	ds_read_b128 v[146:149], v98 offset:4640
	ds_read_b128 v[186:189], v99 offset:18464
	ds_read_b128 v[190:193], v99 offset:23072
	v_mfma_f32_32x32x16_bf16 v[0:15], v[138:141], v[142:145], v[0:15]
	s_waitcnt lgkmcnt(5)
	v_mfma_f32_32x32x16_bf16 v[48:63], v[122:125], v[114:117], v[48:63]
	s_waitcnt vmcnt(7)
	ds_write_b128 v95, v[102:105] offset:36864
	s_waitcnt vmcnt(6)
	ds_write_b128 v95, v[78:81] offset:55296
	s_waitcnt vmcnt(5)
	ds_write_b128 v95, v[106:109] offset:41472
	s_waitcnt vmcnt(4)
	ds_write_b128 v95, v[82:85] offset:59904
	s_waitcnt vmcnt(3)
	ds_write_b128 v95, v[130:133] offset:46080
	s_waitcnt vmcnt(2)
	ds_write_b128 v95, v[86:89] offset:64512
	s_waitcnt vmcnt(1)
	ds_write_b128 v95, v[110:113] offset:50688
	s_waitcnt vmcnt(0)
	ds_write_b128 v100, v[90:93] offset:13824
	ds_read_b128 v[78:81], v99 offset:18496
	ds_read_b128 v[82:85], v98 offset:64
	ds_read_b128 v[86:89], v98 offset:96
	ds_read_b128 v[90:93], v99 offset:18528
	ds_read_b128 v[102:105], v99 offset:23104
	ds_read_b128 v[106:109], v99 offset:23136
	s_waitcnt lgkmcnt(14)
	v_mfma_f32_32x32x16_bf16 v[32:47], v[126:129], v[114:117], v[32:47]
	v_mfma_f32_32x32x16_bf16 v[16:31], v[122:125], v[118:121], v[16:31]
	v_mfma_f32_32x32x16_bf16 v[0:15], v[126:129], v[118:121], v[0:15]
	v_mfma_f32_32x32x16_bf16 v[48:63], v[186:189], v[134:137], v[48:63]
	v_mfma_f32_32x32x16_bf16 v[32:47], v[190:193], v[134:137], v[32:47]
	v_mfma_f32_32x32x16_bf16 v[16:31], v[186:189], v[146:149], v[16:31]
	v_mfma_f32_32x32x16_bf16 v[0:15], v[190:193], v[146:149], v[0:15]
	s_waitcnt lgkmcnt(4)
	v_mfma_f32_32x32x16_bf16 v[48:63], v[78:81], v[82:85], v[48:63]
	s_waitcnt lgkmcnt(1)
	v_mfma_f32_32x32x16_bf16 v[32:47], v[102:105], v[82:85], v[32:47]
	ds_read_b128 v[82:85], v98 offset:4672
	ds_read_b128 v[110:113], v98 offset:4704
	s_waitcnt lgkmcnt(0)
	s_barrier
	v_mfma_f32_32x32x16_bf16 v[16:31], v[78:81], v[82:85], v[16:31]
	v_mfma_f32_32x32x16_bf16 v[0:15], v[102:105], v[82:85], v[0:15]
	v_mfma_f32_32x32x16_bf16 v[48:63], v[90:93], v[86:89], v[48:63]
	v_mfma_f32_32x32x16_bf16 v[32:47], v[106:109], v[86:89], v[32:47]
	v_mfma_f32_32x32x16_bf16 v[16:31], v[90:93], v[110:113], v[16:31]
	ds_read_b128 v[78:81], v96 offset:36864
	ds_read_b128 v[82:85], v96 offset:41472
	ds_read_b128 v[86:89], v97 offset:55296
	ds_read_b128 v[90:93], v97 offset:59904
	ds_read_b128 v[102:105], v98 offset:36896
	ds_read_b128 v[114:117], v98 offset:41504
	ds_read_b128 v[118:121], v99 offset:55328
	ds_read_b128 v[122:125], v99 offset:59936
	v_mfma_f32_32x32x16_bf16 v[0:15], v[106:109], v[110:113], v[0:15]
	s_waitcnt lgkmcnt(5)
	v_mfma_f32_32x32x16_bf16 v[48:63], v[86:89], v[78:81], v[48:63]
	s_mov_b32 s19, 1
	s_mov_b32 s20, 16
	s_waitcnt lgkmcnt(4)
	v_mfma_f32_32x32x16_bf16 v[32:47], v[90:93], v[78:81], v[32:47]
	v_mfma_f32_32x32x16_bf16 v[0:15], v[90:93], v[82:85], v[0:15]
	v_mfma_f32_32x32x16_bf16 v[16:31], v[86:89], v[82:85], v[16:31]
	ds_read_b128 v[78:81], v99 offset:55360
	ds_read_b128 v[82:85], v98 offset:36928
	ds_read_b128 v[86:89], v98 offset:36960
	ds_read_b128 v[90:93], v99 offset:55392
	s_waitcnt lgkmcnt(5)
	v_mfma_f32_32x32x16_bf16 v[48:63], v[118:121], v[102:105], v[48:63]
	s_waitcnt lgkmcnt(4)
	v_mfma_f32_32x32x16_bf16 v[32:47], v[122:125], v[102:105], v[32:47]
	ds_read_b128 v[102:105], v99 offset:59968
	ds_read_b128 v[106:109], v99 offset:60000
	v_mfma_f32_32x32x16_bf16 v[0:15], v[122:125], v[114:117], v[0:15]
	v_mfma_f32_32x32x16_bf16 v[16:31], v[118:121], v[114:117], v[16:31]
	s_waitcnt lgkmcnt(4)
	v_mfma_f32_32x32x16_bf16 v[48:63], v[78:81], v[82:85], v[48:63]
	s_waitcnt lgkmcnt(1)
	v_mfma_f32_32x32x16_bf16 v[32:47], v[102:105], v[82:85], v[32:47]
	ds_read_b128 v[82:85], v98 offset:41536
	ds_read_b128 v[110:113], v98 offset:41568
	s_waitcnt lgkmcnt(0)
	s_barrier
	s_barrier
	v_mfma_f32_32x32x16_bf16 v[0:15], v[102:105], v[82:85], v[0:15]
	v_mfma_f32_32x32x16_bf16 v[16:31], v[78:81], v[82:85], v[16:31]
	v_mfma_f32_32x32x16_bf16 v[48:63], v[90:93], v[86:89], v[48:63]
	v_mfma_f32_32x32x16_bf16 v[32:47], v[106:109], v[86:89], v[32:47]
	s_nop 10
	ds_write_b128 v101, v[48:51]
	ds_write_b128 v101, v[52:55] offset:32
	ds_write_b128 v101, v[56:59] offset:64
	ds_write_b128 v101, v[60:63] offset:96
	ds_write_b128 v101, v[32:35] offset:128
	v_mfma_f32_32x32x16_bf16 v[0:15], v[106:109], v[110:113], v[0:15]
	v_mfma_f32_32x32x16_bf16 v[16:31], v[90:93], v[110:113], v[16:31]
	ds_write_b128 v101, v[36:39] offset:160
	ds_write_b128 v101, v[40:43] offset:192
	ds_write_b128 v101, v[44:47] offset:224
	s_nop 8
	ds_write_b128 v101, v[16:19] offset:16896
	ds_write_b128 v101, v[20:23] offset:16928
	ds_write_b128 v101, v[24:27] offset:16960
	ds_write_b128 v101, v[28:31] offset:16992
	ds_write_b128 v101, v[0:3] offset:17024
	ds_write_b128 v101, v[4:7] offset:17056
	ds_write_b128 v101, v[8:11] offset:17088
	ds_write_b128 v101, v[12:15] offset:17120
	v_or_b32_e32 v0, s18, v94
	v_lshrrev_b32_e32 v1, 5, v156
	v_add_u32_e32 v18, s16, v1
	v_lshlrev_b32_e32 v18, 12, v18
	v_lshl_add_u32 v18, v0, 2, v18
	v_mov_b32_e32 v64, v18
	v_mad_u32_u24 v1, v1, s9, v70
	s_mov_b32 s18, s16
	global_load_dwordx4 v[32:35], v64, s[92:93]
	v_add_u32_e32 v64, 0x8000, v64
	global_load_dwordx4 v[36:39], v64, s[92:93]
	v_add_u32_e32 v64, 0x8000, v64
	global_load_dwordx4 v[40:43], v64, s[92:93]
	v_add_u32_e32 v64, 0x8000, v64
	global_load_dwordx4 v[44:47], v64, s[92:93]
	v_add_u32_e32 v64, 0x8000, v64
	global_load_dwordx4 v[48:51], v64, s[92:93]
	v_add_u32_e32 v64, 0x8000, v64
	global_load_dwordx4 v[52:55], v64, s[92:93]
	v_add_u32_e32 v64, 0x8000, v64
	global_load_dwordx4 v[56:59], v64, s[92:93]
	v_add_u32_e32 v64, 0x8000, v64
	global_load_dwordx4 v[60:63], v64, s[92:93]
	v_add_u32_e32 v64, 0x8000, v64
	s_waitcnt lgkmcnt(0)
	s_barrier
	ds_read_b128 v[2:5], v1
	ds_read_b128 v[6:9], v1 offset:4224
	ds_read_b128 v[10:13], v1 offset:8448
	ds_read_b128 v[14:17], v1 offset:12672
	s_waitcnt vmcnt(7) lgkmcnt(3)
	v_pk_add_f32 v[32:33], v[2:3], v[32:33]
	v_pk_add_f32 v[34:35], v[4:5], v[34:35]
	global_store_dwordx4 v18, v[32:35], s[92:93]
	v_add_u32_e32 v18, 0x8000, v18
	global_load_dwordx4 v[32:35], v64, s[92:93]
	v_add_u32_e32 v64, 0x8000, v64
	ds_read_b128 v[2:5], v1 offset:16896
	s_waitcnt vmcnt(8) lgkmcnt(3)
	v_pk_add_f32 v[36:37], v[6:7], v[36:37]
	v_pk_add_f32 v[38:39], v[8:9], v[38:39]
	global_store_dwordx4 v18, v[36:39], s[92:93]
	v_add_u32_e32 v18, 0x8000, v18
	global_load_dwordx4 v[36:39], v64, s[92:93]
	v_add_u32_e32 v64, 0x8000, v64
	ds_read_b128 v[6:9], v1 offset:21120
	s_waitcnt vmcnt(9) lgkmcnt(3)
	v_pk_add_f32 v[40:41], v[10:11], v[40:41]
	v_pk_add_f32 v[42:43], v[12:13], v[42:43]
	global_store_dwordx4 v18, v[40:43], s[92:93]
	v_add_u32_e32 v18, 0x8000, v18
	global_load_dwordx4 v[40:43], v64, s[92:93]
	v_add_u32_e32 v64, 0x8000, v64
	ds_read_b128 v[10:13], v1 offset:25344
	s_waitcnt vmcnt(10) lgkmcnt(3)
	v_pk_add_f32 v[44:45], v[14:15], v[44:45]
	v_pk_add_f32 v[46:47], v[16:17], v[46:47]
	global_store_dwordx4 v18, v[44:47], s[92:93]
	v_add_u32_e32 v18, 0x8000, v18
	global_load_dwordx4 v[44:47], v64, s[92:93]
	v_add_u32_e32 v64, 0x8000, v64
	ds_read_b128 v[14:17], v1 offset:29568
	s_waitcnt vmcnt(11) lgkmcnt(3)
	v_pk_add_f32 v[48:49], v[2:3], v[48:49]
	v_pk_add_f32 v[50:51], v[4:5], v[50:51]
	global_store_dwordx4 v18, v[48:51], s[92:93]
	v_add_u32_e32 v18, 0x8000, v18
	global_load_dwordx4 v[48:51], v64, s[92:93]
	v_add_u32_e32 v64, 0x8000, v64
	ds_read_b128 v[2:5], v1 offset:33792
	s_waitcnt vmcnt(12) lgkmcnt(3)
	v_pk_add_f32 v[52:53], v[6:7], v[52:53]
	v_pk_add_f32 v[54:55], v[8:9], v[54:55]
	global_store_dwordx4 v18, v[52:55], s[92:93]
	v_add_u32_e32 v18, 0x8000, v18
	global_load_dwordx4 v[52:55], v64, s[92:93]
	v_add_u32_e32 v64, 0x8000, v64
	ds_read_b128 v[6:9], v1 offset:38016
	s_waitcnt vmcnt(13) lgkmcnt(3)
	v_pk_add_f32 v[56:57], v[10:11], v[56:57]
	v_pk_add_f32 v[58:59], v[12:13], v[58:59]
	global_store_dwordx4 v18, v[56:59], s[92:93]
	v_add_u32_e32 v18, 0x8000, v18
	global_load_dwordx4 v[56:59], v64, s[92:93]
	v_add_u32_e32 v64, 0x8000, v64
	ds_read_b128 v[10:13], v1 offset:42240
	s_waitcnt vmcnt(14) lgkmcnt(3)
	v_pk_add_f32 v[60:61], v[14:15], v[60:61]
	v_pk_add_f32 v[62:63], v[16:17], v[62:63]
	global_store_dwordx4 v18, v[60:63], s[92:93]
	v_add_u32_e32 v18, 0x8000, v18
	global_load_dwordx4 v[60:63], v64, s[92:93]
	ds_read_b128 v[14:17], v1 offset:46464
	s_waitcnt vmcnt(14) lgkmcnt(3)
	v_pk_add_f32 v[32:33], v[2:3], v[32:33]
	v_pk_add_f32 v[34:35], v[4:5], v[34:35]
	global_store_dwordx4 v18, v[32:35], s[92:93]
	v_add_u32_e32 v18, 0x8000, v18
	ds_read_b128 v[2:5], v1 offset:50688
	s_waitcnt vmcnt(13) lgkmcnt(3)
	v_pk_add_f32 v[36:37], v[6:7], v[36:37]
	v_pk_add_f32 v[38:39], v[8:9], v[38:39]
	global_store_dwordx4 v18, v[36:39], s[92:93]
	v_add_u32_e32 v18, 0x8000, v18
	ds_read_b128 v[6:9], v1 offset:54912
	s_waitcnt vmcnt(12) lgkmcnt(3)
	v_pk_add_f32 v[40:41], v[10:11], v[40:41]
	v_pk_add_f32 v[42:43], v[12:13], v[42:43]
	global_store_dwordx4 v18, v[40:43], s[92:93]
	v_add_u32_e32 v18, 0x8000, v18
	ds_read_b128 v[10:13], v1 offset:59136
	s_waitcnt vmcnt(11) lgkmcnt(3)
	v_pk_add_f32 v[44:45], v[14:15], v[44:45]
	v_pk_add_f32 v[46:47], v[16:17], v[46:47]
	global_store_dwordx4 v18, v[44:47], s[92:93]
	v_add_u32_e32 v18, 0x8000, v18
	ds_read_b128 v[14:17], v1 offset:63360
	s_waitcnt vmcnt(10) lgkmcnt(3)
	v_pk_add_f32 v[48:49], v[2:3], v[48:49]
	v_pk_add_f32 v[50:51], v[4:5], v[50:51]
	global_store_dwordx4 v18, v[48:51], s[92:93]
	v_add_u32_e32 v18, 0x8000, v18
	s_waitcnt vmcnt(9) lgkmcnt(2)
	v_pk_add_f32 v[52:53], v[6:7], v[52:53]
	v_pk_add_f32 v[54:55], v[8:9], v[54:55]
	global_store_dwordx4 v18, v[52:55], s[92:93]
	v_add_u32_e32 v18, 0x8000, v18
	s_waitcnt vmcnt(8) lgkmcnt(1)
	v_pk_add_f32 v[56:57], v[10:11], v[56:57]
	v_pk_add_f32 v[58:59], v[12:13], v[58:59]
	global_store_dwordx4 v18, v[56:59], s[92:93]
	v_add_u32_e32 v18, 0x8000, v18
	s_waitcnt vmcnt(7) lgkmcnt(0)
	v_pk_add_f32 v[60:61], v[14:15], v[60:61]
	v_pk_add_f32 v[62:63], v[16:17], v[62:63]
	global_store_dwordx4 v18, v[60:63], s[92:93]
	s_branch .LBB0_1048
